# weight-conversion f32 loads marked nt (read-once stream); nothing else changed
# speedup vs baseline: 1.0009x; 1.0009x over previous
.LBB0_11:
	s_lshl_b32 s43, s35, 1
	s_lshl_b32 s44, s34, 1
	v_add_u32_e32 v70, s43, v4
	v_add_u32_e32 v68, s44, v5
	v_add_u32_e32 v72, s44, v7
	v_add_u32_e32 v74, s43, v6
	v_add_u32_e32 v76, s44, v25
	v_add_u32_e32 v78, s43, v34
	v_add_u32_e32 v80, s44, v27
	v_add_u32_e32 v82, s43, v36
	v_add_u32_e32 v84, s44, v29
	v_add_u32_e32 v86, s43, v38
	v_add_u32_e32 v88, s44, v31
	v_add_u32_e32 v90, s43, v40
	v_add_u32_e32 v92, s44, v33
	v_add_u32_e32 v94, s43, v42
	v_add_u32_e32 v96, s44, v35
	v_add_u32_e32 v98, s43, v44
	v_ashrrev_i32_e32 v71, 31, v70
	v_ashrrev_i32_e32 v69, 31, v68
	v_ashrrev_i32_e32 v75, 31, v74
	v_ashrrev_i32_e32 v73, 31, v72
	v_ashrrev_i32_e32 v79, 31, v78
	v_ashrrev_i32_e32 v77, 31, v76
	v_ashrrev_i32_e32 v83, 31, v82
	v_ashrrev_i32_e32 v81, 31, v80
	v_ashrrev_i32_e32 v87, 31, v86
	v_ashrrev_i32_e32 v85, 31, v84
	v_ashrrev_i32_e32 v91, 31, v90
	v_ashrrev_i32_e32 v89, 31, v88
	v_ashrrev_i32_e32 v95, 31, v94
	v_ashrrev_i32_e32 v93, 31, v92
	v_ashrrev_i32_e32 v99, 31, v98
	v_ashrrev_i32_e32 v97, 31, v96
	v_lshlrev_b64 v[70:71], 13, v[70:71]
	v_lshlrev_b64 v[68:69], 13, v[68:69]
	v_lshlrev_b64 v[72:73], 13, v[72:73]
	v_lshlrev_b64 v[74:75], 13, v[74:75]
	v_lshlrev_b64 v[76:77], 13, v[76:77]
	v_lshlrev_b64 v[78:79], 13, v[78:79]
	v_lshlrev_b64 v[80:81], 13, v[80:81]
	v_lshlrev_b64 v[82:83], 13, v[82:83]
	v_lshlrev_b64 v[84:85], 13, v[84:85]
	v_lshlrev_b64 v[86:87], 13, v[86:87]
	v_lshlrev_b64 v[88:89], 13, v[88:89]
	v_lshlrev_b64 v[90:91], 13, v[90:91]
	v_lshlrev_b64 v[92:93], 13, v[92:93]
	v_lshlrev_b64 v[94:95], 13, v[94:95]
	v_lshlrev_b64 v[96:97], 13, v[96:97]
	v_lshlrev_b64 v[98:99], 13, v[98:99]
	v_lshl_add_u64 v[70:71], v[2:3], 0, v[70:71]
	v_lshl_add_u64 v[68:69], v[2:3], 0, v[68:69]
	v_lshl_add_u64 v[74:75], v[2:3], 0, v[74:75]
	v_lshl_add_u64 v[72:73], v[2:3], 0, v[72:73]
	v_lshl_add_u64 v[78:79], v[2:3], 0, v[78:79]
	v_lshl_add_u64 v[76:77], v[2:3], 0, v[76:77]
	v_lshl_add_u64 v[82:83], v[2:3], 0, v[82:83]
	v_lshl_add_u64 v[80:81], v[2:3], 0, v[80:81]
	v_lshl_add_u64 v[86:87], v[2:3], 0, v[86:87]
	v_lshl_add_u64 v[84:85], v[2:3], 0, v[84:85]
	v_lshl_add_u64 v[90:91], v[2:3], 0, v[90:91]
	v_lshl_add_u64 v[88:89], v[2:3], 0, v[88:89]
	v_lshl_add_u64 v[94:95], v[2:3], 0, v[94:95]
	v_lshl_add_u64 v[92:93], v[2:3], 0, v[92:93]
	v_lshl_add_u64 v[98:99], v[2:3], 0, v[98:99]
	v_lshl_add_u64 v[96:97], v[2:3], 0, v[96:97]
	global_load_dword v37, v[70:71], off nt
	global_load_dword v39, v[68:69], off nt
	global_load_dword v41, v[74:75], off nt
	global_load_dword v46, v[72:73], off nt
	global_load_dword v48, v[78:79], off nt
	global_load_dword v67, v[76:77], off nt
	global_load_dword v100, v[82:83], off nt
	global_load_dword v101, v[80:81], off nt
	global_load_dword v102, v[86:87], off nt
	global_load_dword v103, v[84:85], off nt
	global_load_dword v104, v[90:91], off nt
	global_load_dword v105, v[88:89], off nt
	global_load_dword v106, v[94:95], off nt
	global_load_dword v107, v[92:93], off nt
	global_load_dword v108, v[98:99], off nt
	global_load_dword v109, v[96:97], off nt
	s_add_i32 s35, s35, 16
	s_add_i32 s34, s34, 16
	s_add_i32 s41, s41, -16
	v_add_u32_e32 v68, s43, v12
	v_add_u32_e32 v70, s44, v9
	v_add_u32_e32 v74, s44, v11
	v_add_u32_e32 v72, s43, v14
	v_add_u32_e32 v78, s44, v13
	v_add_u32_e32 v76, s43, v16
	v_add_u32_e32 v82, s44, v15
	v_add_u32_e32 v80, s43, v18
	v_add_u32_e32 v86, s44, v17
	v_add_u32_e32 v84, s43, v20
	v_add_u32_e32 v90, s44, v19
	v_add_u32_e32 v88, s43, v22
	v_add_u32_e32 v94, s44, v21
	v_add_u32_e32 v92, s43, v24
	v_add_u32_e32 v98, s44, v23
	v_add_u32_e32 v96, s43, v26
	s_cmp_lg_u32 s41, 0
	v_mad_u64_u32 v[68:69], s[44:45], v68, s62, v[32:33]
	v_mad_u64_u32 v[70:71], s[44:45], v70, s62, v[32:33]
	v_mad_u64_u32 v[72:73], s[44:45], v72, s62, v[32:33]
	v_mad_u64_u32 v[74:75], s[44:45], v74, s62, v[32:33]
	v_mad_u64_u32 v[76:77], s[44:45], v76, s62, v[32:33]
	v_mad_u64_u32 v[78:79], s[44:45], v78, s62, v[32:33]
	v_mad_u64_u32 v[80:81], s[44:45], v80, s62, v[32:33]
	v_mad_u64_u32 v[82:83], s[44:45], v82, s62, v[32:33]
	v_mad_u64_u32 v[84:85], s[44:45], v84, s62, v[32:33]
	v_mad_u64_u32 v[86:87], s[44:45], v86, s62, v[32:33]
	v_mad_u64_u32 v[88:89], s[44:45], v88, s62, v[32:33]
	v_mad_u64_u32 v[90:91], s[44:45], v90, s62, v[32:33]
	v_mad_u64_u32 v[92:93], s[44:45], v92, s62, v[32:33]
	v_mad_u64_u32 v[94:95], s[44:45], v94, s62, v[32:33]
	v_mad_u64_u32 v[96:97], s[44:45], v96, s62, v[32:33]
	v_mad_u64_u32 v[98:99], s[44:45], v98, s62, v[32:33]
	s_waitcnt vmcnt(0)
	ds_write_b32 v68, v37
	s_waitcnt vmcnt(14)
	ds_write_b32 v70, v39
	s_waitcnt vmcnt(13)
	ds_write_b32 v72, v41
	s_waitcnt vmcnt(12)
	ds_write_b32 v74, v46
	s_waitcnt vmcnt(11)
	ds_write_b32 v76, v48
	s_waitcnt vmcnt(10)
	ds_write_b32 v78, v67
	s_waitcnt vmcnt(9)
	ds_write_b32 v80, v100
	s_waitcnt vmcnt(8)
	ds_write_b32 v82, v101
	s_waitcnt vmcnt(7)
	ds_write_b32 v84, v102
	s_waitcnt vmcnt(6)
	ds_write_b32 v86, v103
	s_waitcnt vmcnt(5)
	ds_write_b32 v88, v104
	s_waitcnt vmcnt(4)
	ds_write_b32 v90, v105
	s_waitcnt vmcnt(3)
	ds_write_b32 v92, v106
	s_waitcnt vmcnt(2)
	ds_write_b32 v94, v107
	s_waitcnt vmcnt(1)
	ds_write_b32 v96, v108
	s_waitcnt vmcnt(0)
	ds_write_b32 v98, v109
	s_cbranch_scc1 .LBB0_11
	s_waitcnt lgkmcnt(0)
	ds_read2_b32 v[6:7], v58 offset1:8
	ds_read2_b32 v[34:35], v58 offset0:33 offset1:41
	ds_read2_b32 v[36:37], v58 offset0:66 offset1:74
	ds_read2_b32 v[38:39], v58 offset0:99 offset1:107
	ds_read2_b32 v[40:41], v58 offset0:132 offset1:140
	ds_read2_b32 v[68:69], v58 offset0:165 offset1:173
	s_waitcnt lgkmcnt(5)
	v_bfe_u32 v2, v6, 16, 1
	v_add3_u32 v2, v6, v2, s63
	s_waitcnt lgkmcnt(4)
	v_bfe_u32 v3, v34, 16, 1
	v_lshrrev_b32_e32 v2, 16, v2
	v_add3_u32 v3, v34, v3, s63
	v_and_or_b32 v2, v3, vcc_lo, v2
	s_waitcnt lgkmcnt(3)
	v_bfe_u32 v3, v36, 16, 1
	v_add3_u32 v3, v36, v3, s63
	s_waitcnt lgkmcnt(2)
	v_bfe_u32 v4, v38, 16, 1
	ds_read2_b32 v[70:71], v58 offset0:198 offset1:206
	v_lshrrev_b32_e32 v3, 16, v3
	v_add3_u32 v4, v38, v4, s63
	ds_read2_b32 v[72:73], v58 offset0:231 offset1:239
	v_and_or_b32 v3, v4, vcc_lo, v3
	s_waitcnt lgkmcnt(3)
	v_bfe_u32 v4, v40, 16, 1
	v_add3_u32 v4, v40, v4, s63
	s_waitcnt lgkmcnt(2)
	v_bfe_u32 v5, v68, 16, 1
	v_lshrrev_b32_e32 v4, 16, v4
	v_add3_u32 v5, v68, v5, s63
	v_and_or_b32 v4, v5, vcc_lo, v4
	s_waitcnt lgkmcnt(1)
	v_bfe_u32 v5, v70, 16, 1
	v_add3_u32 v5, v70, v5, s63
	s_waitcnt lgkmcnt(0)
	v_bfe_u32 v6, v72, 16, 1
	v_add_u32_e32 v25, s42, v43
	v_lshrrev_b32_e32 v5, 16, v5
	v_add3_u32 v6, v72, v6, s63
	v_and_or_b32 v5, v6, vcc_lo, v5
	v_and_or_b32 v6, v25, s58, v59
	v_ashrrev_i32_e32 v25, 7, v25
	v_mul_lo_u32 v74, v25, s7
	s_ashr_i32 s41, s40, 31
	v_ashrrev_i32_e32 v75, 31, v74
	v_lshl_add_u64 v[74:75], v[74:75], 0, s[40:41]
	v_lshrrev_b32_e32 v6, 3, v6
	v_lshlrev_b64 v[74:75], 14, v[74:75]
	v_or_b32_e32 v6, v6, v45
	v_lshl_or_b32 v76, v6, 10, v60
	v_mov_b32_e32 v77, v8
	v_lshl_add_u64 v[74:75], s[36:37], 0, v[74:75]
	v_lshl_add_u64 v[74:75], v[74:75], 0, v[76:77]
	global_store_dwordx4 v[74:75], v[2:5], off
	v_bfe_u32 v6, v73, 16, 1
	v_add3_u32 v6, v73, v6, s63
	v_bfe_u32 v2, v7, 16, 1
	v_add3_u32 v2, v7, v2, s63
	v_bfe_u32 v3, v35, 16, 1
	v_lshrrev_b32_e32 v2, 16, v2
	v_add3_u32 v3, v35, v3, s63
	v_and_or_b32 v2, v3, vcc_lo, v2
	v_bfe_u32 v3, v37, 16, 1
	v_add3_u32 v3, v37, v3, s63
	v_bfe_u32 v4, v39, 16, 1
	v_lshrrev_b32_e32 v3, 16, v3
	v_add3_u32 v4, v39, v4, s63
	v_and_or_b32 v3, v4, vcc_lo, v3
	v_bfe_u32 v4, v41, 16, 1
	v_add3_u32 v4, v41, v4, s63
	v_bfe_u32 v5, v69, 16, 1
	v_lshrrev_b32_e32 v4, 16, v4
	v_add3_u32 v5, v69, v5, s63
	v_and_or_b32 v4, v5, vcc_lo, v4
	v_bfe_u32 v5, v71, 16, 1
	v_add3_u32 v5, v71, v5, s63
	v_lshrrev_b32_e32 v5, 16, v5
	v_and_or_b32 v5, v6, vcc_lo, v5
	v_add_u32_e32 v6, s42, v47
	v_and_or_b32 v25, v6, s58, v61
	v_ashrrev_i32_e32 v6, 7, v6
	v_mul_lo_u32 v6, v6, s7
	v_ashrrev_i32_e32 v7, 31, v6
	v_lshl_add_u64 v[6:7], v[6:7], 0, s[40:41]
	v_lshrrev_b32_e32 v25, 3, v25
	v_lshlrev_b64 v[6:7], 14, v[6:7]
	v_or_b32_e32 v25, v25, v45
	v_lshl_or_b32 v34, v25, 10, v62
	v_mov_b32_e32 v35, v8
	v_lshl_add_u64 v[6:7], s[36:37], 0, v[6:7]
	ds_read2_b32 v[36:37], v58 offset0:16 offset1:24
	v_lshl_add_u64 v[6:7], v[6:7], 0, v[34:35]
	global_store_dwordx4 v[6:7], v[2:5], off
	ds_read2_b32 v[6:7], v58 offset0:49 offset1:57
	ds_read2_b32 v[34:35], v58 offset0:82 offset1:90
	ds_read2_b32 v[38:39], v58 offset0:115 offset1:123
	s_waitcnt lgkmcnt(3)
	v_bfe_u32 v2, v36, 16, 1
	v_add3_u32 v2, v36, v2, s63
	s_waitcnt lgkmcnt(2)
	v_bfe_u32 v3, v6, 16, 1
	ds_read2_b32 v[40:41], v58 offset0:148 offset1:156
	v_lshrrev_b32_e32 v2, 16, v2
	v_add3_u32 v3, v6, v3, s63
	ds_read2_b32 v[68:69], v58 offset0:181 offset1:189
	v_and_or_b32 v2, v3, vcc_lo, v2
	s_waitcnt lgkmcnt(3)
	v_bfe_u32 v3, v34, 16, 1
	v_add3_u32 v3, v34, v3, s63
	s_waitcnt lgkmcnt(2)
	v_bfe_u32 v4, v38, 16, 1
	ds_read2_b32 v[70:71], v58 offset0:214 offset1:222
	v_lshrrev_b32_e32 v3, 16, v3
	v_add3_u32 v4, v38, v4, s63
	ds_read2_b32 v[72:73], v58 offset0:247 offset1:255
	v_and_or_b32 v3, v4, vcc_lo, v3
	s_waitcnt lgkmcnt(3)
	v_bfe_u32 v4, v40, 16, 1
	v_add3_u32 v4, v40, v4, s63
	s_waitcnt lgkmcnt(2)
	v_bfe_u32 v5, v68, 16, 1
	v_lshrrev_b32_e32 v4, 16, v4
	v_add3_u32 v5, v68, v5, s63
	v_and_or_b32 v4, v5, vcc_lo, v4
	s_waitcnt lgkmcnt(1)
	v_bfe_u32 v5, v70, 16, 1
	v_add3_u32 v5, v70, v5, s63
	s_waitcnt lgkmcnt(0)
	v_bfe_u32 v6, v72, 16, 1
	v_lshrrev_b32_e32 v5, 16, v5
	v_add3_u32 v6, v72, v6, s63
	v_and_or_b32 v5, v6, vcc_lo, v5
	v_add_u32_e32 v6, s42, v49
	v_and_or_b32 v25, v6, s58, v63
	v_ashrrev_i32_e32 v6, 7, v6
	v_mul_lo_u32 v74, v6, s7
	v_ashrrev_i32_e32 v75, 31, v74
	v_lshl_add_u64 v[74:75], v[74:75], 0, s[40:41]
	v_lshrrev_b32_e32 v6, 3, v25
	v_lshlrev_b64 v[74:75], 14, v[74:75]
	v_or_b32_e32 v6, v6, v45
	v_lshl_or_b32 v76, v6, 10, v64
	v_lshl_add_u64 v[74:75], s[36:37], 0, v[74:75]
	v_lshl_add_u64 v[74:75], v[74:75], 0, v[76:77]
	global_store_dwordx4 v[74:75], v[2:5], off
	v_bfe_u32 v6, v73, 16, 1
	v_add3_u32 v6, v73, v6, s63
	v_bfe_u32 v2, v37, 16, 1
	v_add3_u32 v2, v37, v2, s63
	v_bfe_u32 v3, v7, 16, 1
	v_lshrrev_b32_e32 v2, 16, v2
	v_add3_u32 v3, v7, v3, s63
	v_and_or_b32 v2, v3, vcc_lo, v2
	v_bfe_u32 v3, v35, 16, 1
	v_add3_u32 v3, v35, v3, s63
	v_bfe_u32 v4, v39, 16, 1
	v_lshrrev_b32_e32 v3, 16, v3
	v_add3_u32 v4, v39, v4, s63
	v_and_or_b32 v3, v4, vcc_lo, v3
	v_bfe_u32 v4, v41, 16, 1
	v_add3_u32 v4, v41, v4, s63
	v_bfe_u32 v5, v69, 16, 1
	v_lshrrev_b32_e32 v4, 16, v4
	v_add3_u32 v5, v69, v5, s63
	v_and_or_b32 v4, v5, vcc_lo, v4
	v_bfe_u32 v5, v71, 16, 1
	v_add3_u32 v5, v71, v5, s63
	v_lshrrev_b32_e32 v5, 16, v5
	v_and_or_b32 v5, v6, vcc_lo, v5
	v_add_u32_e32 v6, s42, v50
	v_and_or_b32 v25, v6, s58, v65
	v_ashrrev_i32_e32 v6, 7, v6
	v_mul_lo_u32 v6, v6, s7
	v_ashrrev_i32_e32 v7, 31, v6
	v_lshl_add_u64 v[6:7], v[6:7], 0, s[40:41]
	v_lshrrev_b32_e32 v25, 3, v25
	v_lshlrev_b64 v[6:7], 14, v[6:7]
	v_or_b32_e32 v25, v25, v45
	v_lshl_or_b32 v34, v25, 10, v66
	v_mov_b32_e32 v35, v8
	v_lshl_add_u64 v[6:7], s[36:37], 0, v[6:7]
	v_lshl_add_u64 v[6:7], v[6:7], 0, v[34:35]
	global_store_dwordx4 v[6:7], v[2:5], off
	s_waitcnt lgkmcnt(0)
	s_add_i32 s25, s25, s22
	s_cmpk_lt_i32 s25, 0x1600
	s_cbranch_scc1 .LBB0_10
	s_load_dwordx2 s[34:35], s[10:11], 0x98
	s_load_dwordx2 s[36:37], s[10:11], 0x88
	v_lshlrev_b32_e32 v36, 2, v28
	v_mov_b32_e32 v37, v8
	v_lshlrev_b32_e32 v0, 5, v57
	s_waitcnt lgkmcnt(0)
	s_add_u32 s34, s34, s38
	s_addc_u32 s35, s35, s39
	s_add_u32 s40, s8, 0xae00000
	s_addc_u32 s41, s9, 0
	s_lshl_b64 s[42:43], s[14:15], 2
	s_add_u32 s44, s36, s42
	s_addc_u32 s45, s37, s43
	s_cmp_lg_u64 s[36:37], 0
	v_mov_b32_e32 v1, v8
	v_lshl_add_u64 v[38:39], s[34:35], 0, v[36:37]
	s_cselect_b64 s[42:43], -1, 0
	v_lshl_add_u64 v[34:35], s[44:45], 0, v[0:1]
	s_mov_b32 s25, s51
	s_branch .LBB0_16

.LBB0_17:
	s_lshl_b32 s47, s36, 1
	s_lshl_b32 s48, s35, 1
	v_add_u32_e32 v41, s47, v2
	v_add_u32_e32 v37, s48, v3
	v_add_u32_e32 v67, s48, v5
	v_add_u32_e32 v72, s47, v4
	v_add_u32_e32 v78, s48, v7
	v_add_u32_e32 v76, s47, v6
	v_add_u32_e32 v82, s48, v25
	v_add_u32_e32 v80, s47, v40
	v_add_u32_e32 v86, s48, v27
	v_add_u32_e32 v84, s47, v42
	v_add_u32_e32 v90, s48, v29
	v_add_u32_e32 v88, s47, v44
	v_add_u32_e32 v94, s48, v31
	v_add_u32_e32 v92, s47, v46
	v_add_u32_e32 v98, s48, v33
	v_add_u32_e32 v96, s47, v48
	v_mad_i64_i32 v[68:69], s[52:53], v41, s20, v[0:1]
	v_mad_i64_i32 v[70:71], s[52:53], v37, s20, v[0:1]
	v_mad_i64_i32 v[72:73], s[52:53], v72, s20, v[0:1]
	v_mad_i64_i32 v[74:75], s[52:53], v67, s20, v[0:1]
	v_mad_i64_i32 v[76:77], s[52:53], v76, s20, v[0:1]
	v_mad_i64_i32 v[78:79], s[52:53], v78, s20, v[0:1]
	v_mad_i64_i32 v[80:81], s[52:53], v80, s20, v[0:1]
	v_mad_i64_i32 v[82:83], s[52:53], v82, s20, v[0:1]
	v_mad_i64_i32 v[84:85], s[52:53], v84, s20, v[0:1]
	v_mad_i64_i32 v[86:87], s[52:53], v86, s20, v[0:1]
	v_mad_i64_i32 v[88:89], s[52:53], v88, s20, v[0:1]
	v_mad_i64_i32 v[90:91], s[52:53], v90, s20, v[0:1]
	v_mad_i64_i32 v[92:93], s[52:53], v92, s20, v[0:1]
	v_mad_i64_i32 v[94:95], s[52:53], v94, s20, v[0:1]
	v_mad_i64_i32 v[96:97], s[52:53], v96, s20, v[0:1]
	v_mad_i64_i32 v[98:99], s[52:53], v98, s20, v[0:1]
	global_load_dword v37, v[68:69], off nt
	global_load_dword v41, v[70:71], off nt
	global_load_dword v67, v[72:73], off nt
	global_load_dword v100, v[74:75], off nt
	global_load_dword v101, v[76:77], off nt
	global_load_dword v102, v[78:79], off nt
	global_load_dword v103, v[80:81], off nt
	global_load_dword v104, v[82:83], off nt
	global_load_dword v105, v[84:85], off nt
	global_load_dword v106, v[86:87], off nt
	global_load_dword v107, v[88:89], off nt
	global_load_dword v108, v[90:91], off nt
	global_load_dword v109, v[92:93], off nt
	global_load_dword v110, v[94:95], off nt
	global_load_dword v111, v[96:97], off nt
	global_load_dword v112, v[98:99], off nt
	s_add_i32 s36, s36, 16
	s_add_i32 s35, s35, 16
	s_add_i32 s37, s37, -16
	v_add_u32_e32 v68, s47, v12
	v_add_u32_e32 v70, s48, v9
	v_add_u32_e32 v74, s48, v11
	v_add_u32_e32 v72, s47, v14
	v_add_u32_e32 v78, s48, v13
	v_add_u32_e32 v76, s47, v16
	v_add_u32_e32 v82, s48, v15
	v_add_u32_e32 v80, s47, v18
	v_add_u32_e32 v86, s48, v17
	v_add_u32_e32 v84, s47, v20
	v_add_u32_e32 v90, s48, v19
	v_add_u32_e32 v88, s47, v22
	v_add_u32_e32 v94, s48, v21
	v_add_u32_e32 v92, s47, v24
	v_add_u32_e32 v98, s48, v23
	v_add_u32_e32 v96, s47, v26
	s_cmp_lg_u32 s37, 0
	v_mad_u64_u32 v[68:69], s[52:53], v68, s62, v[32:33]
	v_mad_u64_u32 v[70:71], s[52:53], v70, s62, v[32:33]
	v_mad_u64_u32 v[72:73], s[52:53], v72, s62, v[32:33]
	v_mad_u64_u32 v[74:75], s[52:53], v74, s62, v[32:33]
	v_mad_u64_u32 v[76:77], s[52:53], v76, s62, v[32:33]
	v_mad_u64_u32 v[78:79], s[52:53], v78, s62, v[32:33]
	v_mad_u64_u32 v[80:81], s[52:53], v80, s62, v[32:33]
	v_mad_u64_u32 v[82:83], s[52:53], v82, s62, v[32:33]
	v_mad_u64_u32 v[84:85], s[52:53], v84, s62, v[32:33]
	v_mad_u64_u32 v[86:87], s[52:53], v86, s62, v[32:33]
	v_mad_u64_u32 v[88:89], s[52:53], v88, s62, v[32:33]
	v_mad_u64_u32 v[90:91], s[52:53], v90, s62, v[32:33]
	v_mad_u64_u32 v[92:93], s[52:53], v92, s62, v[32:33]
	v_mad_u64_u32 v[94:95], s[52:53], v94, s62, v[32:33]
	v_mad_u64_u32 v[96:97], s[52:53], v96, s62, v[32:33]
	v_mad_u64_u32 v[98:99], s[52:53], v98, s62, v[32:33]
	s_waitcnt vmcnt(15)
	ds_write_b32 v68, v37
	s_waitcnt vmcnt(14)
	ds_write_b32 v70, v41
	s_waitcnt vmcnt(13)
	ds_write_b32 v72, v67
	s_waitcnt vmcnt(12)
	ds_write_b32 v74, v100
	s_waitcnt vmcnt(11)
	ds_write_b32 v76, v101
	s_waitcnt vmcnt(10)
	ds_write_b32 v78, v102
	s_waitcnt vmcnt(9)
	ds_write_b32 v80, v103
	s_waitcnt vmcnt(8)
	ds_write_b32 v82, v104
	s_waitcnt vmcnt(7)
	ds_write_b32 v84, v105
	s_waitcnt vmcnt(6)
	ds_write_b32 v86, v106
	s_waitcnt vmcnt(5)
	ds_write_b32 v88, v107
	s_waitcnt vmcnt(4)
	ds_write_b32 v90, v108
	s_waitcnt vmcnt(3)
	ds_write_b32 v92, v109
	s_waitcnt vmcnt(2)
	ds_write_b32 v94, v110
	s_waitcnt vmcnt(1)
	ds_write_b32 v96, v111
	s_waitcnt vmcnt(0)
	ds_write_b32 v98, v112
	s_cbranch_scc1 .LBB0_17
	v_cndmask_b32_e64 v0, 0, 1, s[42:43]
	v_cmp_ne_u32_e64 s[36:37], 1, v0
	s_andn2_b64 vcc, exec, s[42:43]
	s_cbranch_vccz .LBB0_14
	v_mov_b32_e32 v0, 1.0
	v_mov_b32_e32 v40, 1.0
	v_mov_b32_e32 v1, v0
	v_mov_b32_e32 v41, v0
	v_mov_b32_e32 v4, v0
	v_mov_b32_e32 v2, v0
	v_mov_b32_e32 v5, v0
	v_mov_b32_e32 v3, v0
	s_branch .LBB0_15

.LBB0_24:
	s_lshl_b32 s45, s43, 1
	s_lshl_b32 s48, s35, 1
	v_add_u32_e32 v41, s45, v2
	v_add_u32_e32 v39, s48, v3
	v_add_u32_e32 v48, s48, v5
	v_add_u32_e32 v67, s45, v4
	v_add_u32_e32 v78, s48, v7
	v_add_u32_e32 v76, s45, v6
	v_add_u32_e32 v82, s48, v25
	v_add_u32_e32 v80, s45, v38
	v_add_u32_e32 v86, s48, v27
	v_add_u32_e32 v84, s45, v40
	v_add_u32_e32 v90, s48, v29
	v_add_u32_e32 v88, s45, v42
	v_add_u32_e32 v94, s48, v31
	v_add_u32_e32 v92, s45, v44
	v_add_u32_e32 v98, s48, v33
	v_add_u32_e32 v96, s45, v46
	v_mad_i64_i32 v[68:69], s[46:47], v41, s20, v[0:1]
	v_mad_i64_i32 v[70:71], s[46:47], v39, s20, v[0:1]
	v_mad_i64_i32 v[72:73], s[46:47], v67, s20, v[0:1]
	v_mad_i64_i32 v[74:75], s[46:47], v48, s20, v[0:1]
	v_mad_i64_i32 v[76:77], s[46:47], v76, s20, v[0:1]
	v_mad_i64_i32 v[78:79], s[46:47], v78, s20, v[0:1]
	v_mad_i64_i32 v[80:81], s[46:47], v80, s20, v[0:1]
	v_mad_i64_i32 v[82:83], s[46:47], v82, s20, v[0:1]
	v_mad_i64_i32 v[84:85], s[46:47], v84, s20, v[0:1]
	v_mad_i64_i32 v[86:87], s[46:47], v86, s20, v[0:1]
	v_mad_i64_i32 v[88:89], s[46:47], v88, s20, v[0:1]
	v_mad_i64_i32 v[90:91], s[46:47], v90, s20, v[0:1]
	v_mad_i64_i32 v[92:93], s[46:47], v92, s20, v[0:1]
	v_mad_i64_i32 v[94:95], s[46:47], v94, s20, v[0:1]
	v_mad_i64_i32 v[96:97], s[46:47], v96, s20, v[0:1]
	v_mad_i64_i32 v[98:99], s[46:47], v98, s20, v[0:1]
	global_load_dword v39, v[68:69], off nt
	global_load_dword v41, v[70:71], off nt
	global_load_dword v48, v[72:73], off nt
	global_load_dword v67, v[74:75], off nt
	global_load_dword v100, v[76:77], off nt
	global_load_dword v101, v[78:79], off nt
	global_load_dword v102, v[80:81], off nt
	global_load_dword v103, v[82:83], off nt
	global_load_dword v104, v[84:85], off nt
	global_load_dword v105, v[86:87], off nt
	global_load_dword v106, v[88:89], off nt
	global_load_dword v107, v[90:91], off nt
	global_load_dword v108, v[92:93], off nt
	global_load_dword v109, v[94:95], off nt
	global_load_dword v110, v[96:97], off nt
	global_load_dword v111, v[98:99], off nt
	s_add_i32 s43, s43, 16
	s_add_i32 s35, s35, 16
	s_add_i32 s44, s44, -16
	v_add_u32_e32 v68, s45, v12
	v_add_u32_e32 v70, s48, v9
	v_add_u32_e32 v74, s48, v11
	v_add_u32_e32 v72, s45, v14
	v_add_u32_e32 v78, s48, v13
	v_add_u32_e32 v76, s45, v16
	v_add_u32_e32 v82, s48, v15
	v_add_u32_e32 v80, s45, v18
	v_add_u32_e32 v86, s48, v17
	v_add_u32_e32 v84, s45, v20
	v_add_u32_e32 v90, s48, v19
	v_add_u32_e32 v88, s45, v22
	v_add_u32_e32 v94, s48, v21
	v_add_u32_e32 v92, s45, v24
	v_add_u32_e32 v98, s48, v23
	v_add_u32_e32 v96, s45, v26
	s_cmp_lg_u32 s44, 0
	v_mad_u64_u32 v[68:69], s[46:47], v68, s62, v[32:33]
	v_mad_u64_u32 v[70:71], s[46:47], v70, s62, v[32:33]
	v_mad_u64_u32 v[72:73], s[46:47], v72, s62, v[32:33]
	v_mad_u64_u32 v[74:75], s[46:47], v74, s62, v[32:33]
	v_mad_u64_u32 v[76:77], s[46:47], v76, s62, v[32:33]
	v_mad_u64_u32 v[78:79], s[46:47], v78, s62, v[32:33]
	v_mad_u64_u32 v[80:81], s[46:47], v80, s62, v[32:33]
	v_mad_u64_u32 v[82:83], s[46:47], v82, s62, v[32:33]
	v_mad_u64_u32 v[84:85], s[46:47], v84, s62, v[32:33]
	v_mad_u64_u32 v[86:87], s[46:47], v86, s62, v[32:33]
	v_mad_u64_u32 v[88:89], s[46:47], v88, s62, v[32:33]
	v_mad_u64_u32 v[90:91], s[46:47], v90, s62, v[32:33]
	v_mad_u64_u32 v[92:93], s[46:47], v92, s62, v[32:33]
	v_mad_u64_u32 v[94:95], s[46:47], v94, s62, v[32:33]
	v_mad_u64_u32 v[96:97], s[46:47], v96, s62, v[32:33]
	v_mad_u64_u32 v[98:99], s[46:47], v98, s62, v[32:33]
	s_waitcnt vmcnt(15)
	ds_write_b32 v68, v39
	s_waitcnt vmcnt(14)
	ds_write_b32 v70, v41
	s_waitcnt vmcnt(13)
	ds_write_b32 v72, v48
	s_waitcnt vmcnt(12)
	ds_write_b32 v74, v67
	s_waitcnt vmcnt(11)
	ds_write_b32 v76, v100
	s_waitcnt vmcnt(10)
	ds_write_b32 v78, v101
	s_waitcnt vmcnt(9)
	ds_write_b32 v80, v102
	s_waitcnt vmcnt(8)
	ds_write_b32 v82, v103
	s_waitcnt vmcnt(7)
	ds_write_b32 v84, v104
	s_waitcnt vmcnt(6)
	ds_write_b32 v86, v105
	s_waitcnt vmcnt(5)
	ds_write_b32 v88, v106
	s_waitcnt vmcnt(4)
	ds_write_b32 v90, v107
	s_waitcnt vmcnt(3)
	ds_write_b32 v92, v108
	s_waitcnt vmcnt(2)
	ds_write_b32 v94, v109
	s_waitcnt vmcnt(1)
	ds_write_b32 v96, v110
	s_waitcnt vmcnt(0)
	ds_write_b32 v98, v111
	s_cbranch_scc1 .LBB0_24
	s_and_b64 vcc, exec, s[36:37]
	s_cbranch_vccz .LBB0_21
	v_mov_b32_e32 v0, 1.0
	v_mov_b32_e32 v38, 1.0
	v_mov_b32_e32 v1, v0
	v_mov_b32_e32 v39, v0
	v_mov_b32_e32 v4, v0
	v_mov_b32_e32 v2, v0
	v_mov_b32_e32 v5, v0
	v_mov_b32_e32 v3, v0
	s_branch .LBB0_22

.LBB0_30:
	s_lshl_b32 s45, s35, 1
	s_lshl_b32 s46, s34, 1
	v_add_u32_e32 v66, s45, v6
	v_add_u32_e32 v64, s46, v19
	v_add_u32_e32 v68, s46, v21
	v_add_u32_e32 v70, s45, v34
	v_add_u32_e32 v72, s46, v23
	v_add_u32_e32 v74, s45, v36
	v_add_u32_e32 v76, s46, v25
	v_add_u32_e32 v78, s45, v38
	v_add_u32_e32 v80, s46, v27
	v_add_u32_e32 v82, s45, v40
	v_add_u32_e32 v84, s46, v29
	v_add_u32_e32 v86, s45, v42
	v_add_u32_e32 v88, s46, v31
	v_add_u32_e32 v90, s45, v44
	v_add_u32_e32 v92, s46, v35
	v_add_u32_e32 v94, s45, v46
	v_ashrrev_i32_e32 v67, 31, v66
	v_ashrrev_i32_e32 v65, 31, v64
	v_ashrrev_i32_e32 v71, 31, v70
	v_ashrrev_i32_e32 v69, 31, v68
	v_ashrrev_i32_e32 v75, 31, v74
	v_ashrrev_i32_e32 v73, 31, v72
	v_ashrrev_i32_e32 v79, 31, v78
	v_ashrrev_i32_e32 v77, 31, v76
	v_ashrrev_i32_e32 v83, 31, v82
	v_ashrrev_i32_e32 v81, 31, v80
	v_ashrrev_i32_e32 v87, 31, v86
	v_ashrrev_i32_e32 v85, 31, v84
	v_ashrrev_i32_e32 v91, 31, v90
	v_ashrrev_i32_e32 v89, 31, v88
	v_ashrrev_i32_e32 v95, 31, v94
	v_ashrrev_i32_e32 v93, 31, v92
	v_lshlrev_b64 v[66:67], 13, v[66:67]
	v_lshlrev_b64 v[64:65], 13, v[64:65]
	v_lshlrev_b64 v[68:69], 13, v[68:69]
	v_lshlrev_b64 v[70:71], 13, v[70:71]
	v_lshlrev_b64 v[72:73], 13, v[72:73]
	v_lshlrev_b64 v[74:75], 13, v[74:75]
	v_lshlrev_b64 v[76:77], 13, v[76:77]
	v_lshlrev_b64 v[78:79], 13, v[78:79]
	v_lshlrev_b64 v[80:81], 13, v[80:81]
	v_lshlrev_b64 v[82:83], 13, v[82:83]
	v_lshlrev_b64 v[84:85], 13, v[84:85]
	v_lshlrev_b64 v[86:87], 13, v[86:87]
	v_lshlrev_b64 v[88:89], 13, v[88:89]
	v_lshlrev_b64 v[90:91], 13, v[90:91]
	v_lshlrev_b64 v[92:93], 13, v[92:93]
	v_lshlrev_b64 v[94:95], 13, v[94:95]
	v_lshl_add_u64 v[66:67], v[32:33], 0, v[66:67]
	v_lshl_add_u64 v[64:65], v[32:33], 0, v[64:65]
	v_lshl_add_u64 v[70:71], v[32:33], 0, v[70:71]
	v_lshl_add_u64 v[68:69], v[32:33], 0, v[68:69]
	v_lshl_add_u64 v[74:75], v[32:33], 0, v[74:75]
	v_lshl_add_u64 v[72:73], v[32:33], 0, v[72:73]
	v_lshl_add_u64 v[78:79], v[32:33], 0, v[78:79]
	v_lshl_add_u64 v[76:77], v[32:33], 0, v[76:77]
	v_lshl_add_u64 v[82:83], v[32:33], 0, v[82:83]
	v_lshl_add_u64 v[80:81], v[32:33], 0, v[80:81]
	v_lshl_add_u64 v[86:87], v[32:33], 0, v[86:87]
	v_lshl_add_u64 v[84:85], v[32:33], 0, v[84:85]
	v_lshl_add_u64 v[90:91], v[32:33], 0, v[90:91]
	v_lshl_add_u64 v[88:89], v[32:33], 0, v[88:89]
	v_lshl_add_u64 v[94:95], v[32:33], 0, v[94:95]
	v_lshl_add_u64 v[92:93], v[32:33], 0, v[92:93]
	global_load_dword v63, v[66:67], off nt
	global_load_dword v96, v[64:65], off nt
	global_load_dword v97, v[70:71], off nt
	global_load_dword v98, v[68:69], off nt
	global_load_dword v99, v[74:75], off nt
	global_load_dword v100, v[72:73], off nt
	global_load_dword v101, v[78:79], off nt
	global_load_dword v102, v[76:77], off nt
	global_load_dword v103, v[82:83], off nt
	global_load_dword v104, v[80:81], off nt
	global_load_dword v105, v[86:87], off nt
	global_load_dword v106, v[84:85], off nt
	global_load_dword v107, v[90:91], off nt
	global_load_dword v108, v[88:89], off nt
	global_load_dword v109, v[94:95], off nt
	global_load_dword v110, v[92:93], off nt
	s_add_i32 s35, s35, 16
	s_add_i32 s34, s34, 16
	s_add_i32 s43, s43, -16
	v_add_u32_e32 v64, s45, v12
	v_add_u32_e32 v66, s46, v1
	v_add_u32_e32 v70, s46, v3
	v_add_u32_e32 v68, s45, v14
	v_add_u32_e32 v74, s46, v7
	v_add_u32_e32 v72, s45, v16
	v_add_u32_e32 v78, s46, v9
	v_add_u32_e32 v76, s45, v18
	v_add_u32_e32 v82, s46, v11
	v_add_u32_e32 v80, s45, v20
	v_add_u32_e32 v86, s46, v13
	v_add_u32_e32 v84, s45, v22
	v_add_u32_e32 v90, s46, v15
	v_add_u32_e32 v88, s45, v24
	v_add_u32_e32 v94, s46, v17
	v_add_u32_e32 v92, s45, v26
	s_cmp_lg_u32 s43, 0
	v_mad_u64_u32 v[64:65], s[46:47], v64, s62, v[2:3]
	v_mad_u64_u32 v[66:67], s[46:47], v66, s62, v[2:3]
	v_mad_u64_u32 v[68:69], s[46:47], v68, s62, v[2:3]
	v_mad_u64_u32 v[70:71], s[46:47], v70, s62, v[2:3]
	v_mad_u64_u32 v[72:73], s[46:47], v72, s62, v[2:3]
	v_mad_u64_u32 v[74:75], s[46:47], v74, s62, v[2:3]
	v_mad_u64_u32 v[76:77], s[46:47], v76, s62, v[2:3]
	v_mad_u64_u32 v[78:79], s[46:47], v78, s62, v[2:3]
	v_mad_u64_u32 v[80:81], s[46:47], v80, s62, v[2:3]
	v_mad_u64_u32 v[82:83], s[46:47], v82, s62, v[2:3]
	v_mad_u64_u32 v[84:85], s[46:47], v84, s62, v[2:3]
	v_mad_u64_u32 v[86:87], s[46:47], v86, s62, v[2:3]
	v_mad_u64_u32 v[88:89], s[46:47], v88, s62, v[2:3]
	v_mad_u64_u32 v[90:91], s[46:47], v90, s62, v[2:3]
	v_mad_u64_u32 v[92:93], s[46:47], v92, s62, v[2:3]
	v_mad_u64_u32 v[94:95], s[46:47], v94, s62, v[2:3]
	s_waitcnt vmcnt(0)
	ds_write_b32 v64, v63
	s_waitcnt vmcnt(14)
	ds_write_b32 v66, v96
	s_waitcnt vmcnt(13)
	ds_write_b32 v68, v97
	s_waitcnt vmcnt(12)
	ds_write_b32 v70, v98
	s_waitcnt vmcnt(11)
	ds_write_b32 v72, v99
	s_waitcnt vmcnt(10)
	ds_write_b32 v74, v100
	s_waitcnt vmcnt(9)
	ds_write_b32 v76, v101
	s_waitcnt vmcnt(8)
	ds_write_b32 v78, v102
	s_waitcnt vmcnt(7)
	ds_write_b32 v80, v103
	s_waitcnt vmcnt(6)
	ds_write_b32 v82, v104
	s_waitcnt vmcnt(5)
	ds_write_b32 v84, v105
	s_waitcnt vmcnt(4)
	ds_write_b32 v86, v106
	s_waitcnt vmcnt(3)
	ds_write_b32 v88, v107
	s_waitcnt vmcnt(2)
	ds_write_b32 v90, v108
	s_waitcnt vmcnt(1)
	ds_write_b32 v92, v109
	s_waitcnt vmcnt(0)
	ds_write_b32 v94, v110
	s_cbranch_scc1 .LBB0_30
	s_waitcnt lgkmcnt(0)
	ds_read2_b32 v[64:65], v37 offset1:8
	ds_read2_b32 v[66:67], v37 offset0:33 offset1:41
	ds_read2_b32 v[68:69], v37 offset0:66 offset1:74
	ds_read2_b32 v[70:71], v37 offset0:99 offset1:107
	ds_read2_b32 v[72:73], v37 offset0:132 offset1:140
	ds_read2_b32 v[74:75], v37 offset0:165 offset1:173
	s_waitcnt lgkmcnt(5)
	v_bfe_u32 v19, v64, 16, 1
	v_add3_u32 v19, v64, v19, s63
	s_waitcnt lgkmcnt(4)
	v_bfe_u32 v21, v66, 16, 1
	v_lshrrev_b32_e32 v19, 16, v19
	v_add3_u32 v21, v66, v21, s63
	v_and_or_b32 v32, v21, vcc_lo, v19
	s_waitcnt lgkmcnt(3)
	v_bfe_u32 v19, v68, 16, 1
	v_add3_u32 v19, v68, v19, s63
	s_waitcnt lgkmcnt(2)
	v_bfe_u32 v21, v70, 16, 1
	ds_read2_b32 v[76:77], v37 offset0:198 offset1:206
	v_lshrrev_b32_e32 v19, 16, v19
	v_add3_u32 v21, v70, v21, s63
	ds_read2_b32 v[78:79], v37 offset0:231 offset1:239
	v_and_or_b32 v33, v21, vcc_lo, v19
	s_waitcnt lgkmcnt(3)
	v_bfe_u32 v19, v72, 16, 1
	v_add3_u32 v19, v72, v19, s63
	s_waitcnt lgkmcnt(2)
	v_bfe_u32 v21, v74, 16, 1
	v_lshrrev_b32_e32 v19, 16, v19
	v_add3_u32 v21, v74, v21, s63
	v_and_or_b32 v34, v21, vcc_lo, v19
	s_waitcnt lgkmcnt(1)
	v_bfe_u32 v19, v76, 16, 1
	v_add3_u32 v19, v76, v19, s63
	s_waitcnt lgkmcnt(0)
	v_bfe_u32 v21, v78, 16, 1
	v_add_u32_e32 v6, s42, v43
	v_lshrrev_b32_e32 v19, 16, v19
	v_add3_u32 v21, v78, v21, s63
	v_and_or_b32 v35, v21, vcc_lo, v19
	v_and_or_b32 v19, v6, s58, v39
	v_ashrrev_i32_e32 v80, 7, v6
	v_ashrrev_i32_e32 v81, 31, v80
	v_lshrrev_b32_e32 v6, 3, v19
	s_ashr_i32 s45, s44, 31
	v_lshlrev_b64 v[80:81], 19, v[80:81]
	v_or_b32_e32 v6, v6, v45
	s_lshl_b64 s[34:35], s[44:45], 14
	v_lshl_or_b32 v82, v6, 10, v41
	v_lshl_add_u64 v[80:81], s[40:41], 0, v[80:81]
	v_bfe_u32 v6, v65, 16, 1
	v_mov_b32_e32 v83, v8
	v_lshl_add_u64 v[80:81], v[80:81], 0, s[34:35]
	v_add3_u32 v6, v65, v6, s63
	v_bfe_u32 v19, v67, 16, 1
	v_lshl_add_u64 v[80:81], v[80:81], 0, v[82:83]
	v_lshrrev_b32_e32 v6, 16, v6
	v_add3_u32 v19, v67, v19, s63
	global_store_dwordx4 v[80:81], v[32:35], off
	v_mov_b32_e32 v67, v8
	s_add_i32 s25, s25, s22
	v_and_or_b32 v32, v19, vcc_lo, v6
	v_bfe_u32 v6, v69, 16, 1
	v_add3_u32 v6, v69, v6, s63
	v_bfe_u32 v19, v71, 16, 1
	v_lshrrev_b32_e32 v6, 16, v6
	v_add3_u32 v19, v71, v19, s63
	v_and_or_b32 v33, v19, vcc_lo, v6
	v_bfe_u32 v6, v73, 16, 1
	v_add3_u32 v6, v73, v6, s63
	v_bfe_u32 v19, v75, 16, 1
	v_lshrrev_b32_e32 v6, 16, v6
	v_add3_u32 v19, v75, v19, s63
	v_and_or_b32 v34, v19, vcc_lo, v6
	v_bfe_u32 v6, v77, 16, 1
	v_add3_u32 v6, v77, v6, s63
	v_bfe_u32 v19, v79, 16, 1
	v_lshrrev_b32_e32 v6, 16, v6
	v_add3_u32 v19, v79, v19, s63
	v_and_or_b32 v35, v19, vcc_lo, v6
	v_add_u32_e32 v6, s42, v47
	v_ashrrev_i32_e32 v64, 7, v6
	v_and_or_b32 v19, v6, s58, v48
	v_ashrrev_i32_e32 v65, 31, v64
	v_lshlrev_b64 v[64:65], 19, v[64:65]
	v_lshrrev_b32_e32 v6, 3, v19
	v_or_b32_e32 v6, v6, v45
	v_lshl_add_u64 v[64:65], s[40:41], 0, v[64:65]
	v_lshl_or_b32 v66, v6, 10, v58
	v_lshl_add_u64 v[64:65], v[64:65], 0, s[34:35]
	ds_read2_b32 v[68:69], v37 offset0:16 offset1:24
	v_lshl_add_u64 v[64:65], v[64:65], 0, v[66:67]
	global_store_dwordx4 v[64:65], v[32:35], off
	ds_read2_b32 v[64:65], v37 offset0:49 offset1:57
	ds_read2_b32 v[66:67], v37 offset0:82 offset1:90
	ds_read2_b32 v[70:71], v37 offset0:115 offset1:123
	s_waitcnt lgkmcnt(3)
	v_bfe_u32 v6, v68, 16, 1
	v_add3_u32 v6, v68, v6, s63
	s_waitcnt lgkmcnt(2)
	v_bfe_u32 v19, v64, 16, 1
	ds_read2_b32 v[72:73], v37 offset0:148 offset1:156
	v_lshrrev_b32_e32 v6, 16, v6
	v_add3_u32 v19, v64, v19, s63
	ds_read2_b32 v[74:75], v37 offset0:181 offset1:189
	v_and_or_b32 v32, v19, vcc_lo, v6
	s_waitcnt lgkmcnt(3)
	v_bfe_u32 v6, v66, 16, 1
	v_add3_u32 v6, v66, v6, s63
	s_waitcnt lgkmcnt(2)
	v_bfe_u32 v19, v70, 16, 1
	ds_read2_b32 v[76:77], v37 offset0:214 offset1:222
	v_lshrrev_b32_e32 v6, 16, v6
	v_add3_u32 v19, v70, v19, s63
	ds_read2_b32 v[78:79], v37 offset0:247 offset1:255
	v_and_or_b32 v33, v19, vcc_lo, v6
	s_waitcnt lgkmcnt(3)
	v_bfe_u32 v6, v72, 16, 1
	v_add3_u32 v6, v72, v6, s63
	s_waitcnt lgkmcnt(2)
	v_bfe_u32 v19, v74, 16, 1
	v_lshrrev_b32_e32 v6, 16, v6
	v_add3_u32 v19, v74, v19, s63
	v_and_or_b32 v34, v19, vcc_lo, v6
	s_waitcnt lgkmcnt(1)
	v_bfe_u32 v6, v76, 16, 1
	v_add3_u32 v6, v76, v6, s63
	s_waitcnt lgkmcnt(0)
	v_bfe_u32 v19, v78, 16, 1
	v_lshrrev_b32_e32 v6, 16, v6
	v_add3_u32 v19, v78, v19, s63
	v_and_or_b32 v35, v19, vcc_lo, v6
	v_add_u32_e32 v6, s42, v49
	v_and_or_b32 v19, v6, s58, v59
	v_ashrrev_i32_e32 v80, 7, v6
	v_ashrrev_i32_e32 v81, 31, v80
	v_lshrrev_b32_e32 v6, 3, v19
	v_lshlrev_b64 v[80:81], 19, v[80:81]
	v_or_b32_e32 v6, v6, v45
	v_lshl_or_b32 v82, v6, 10, v60
	v_lshl_add_u64 v[80:81], s[40:41], 0, v[80:81]
	v_bfe_u32 v6, v69, 16, 1
	v_lshl_add_u64 v[80:81], v[80:81], 0, s[34:35]
	v_add3_u32 v6, v69, v6, s63
	v_bfe_u32 v19, v65, 16, 1
	v_lshl_add_u64 v[80:81], v[80:81], 0, v[82:83]
	v_lshrrev_b32_e32 v6, 16, v6
	v_add3_u32 v19, v65, v19, s63
	global_store_dwordx4 v[80:81], v[32:35], off
	s_cmpk_lt_i32 s25, 0x800
	s_nop 0
	v_and_or_b32 v32, v19, vcc_lo, v6
	v_bfe_u32 v6, v67, 16, 1
	v_add3_u32 v6, v67, v6, s63
	v_bfe_u32 v19, v71, 16, 1
	v_lshrrev_b32_e32 v6, 16, v6
	v_add3_u32 v19, v71, v19, s63
	v_and_or_b32 v33, v19, vcc_lo, v6
	v_bfe_u32 v6, v73, 16, 1
	v_add3_u32 v6, v73, v6, s63
	v_bfe_u32 v19, v75, 16, 1
	v_lshrrev_b32_e32 v6, 16, v6
	v_add3_u32 v19, v75, v19, s63
	v_and_or_b32 v34, v19, vcc_lo, v6
	v_bfe_u32 v6, v77, 16, 1
	v_add3_u32 v6, v77, v6, s63
	v_bfe_u32 v19, v79, 16, 1
	v_lshrrev_b32_e32 v6, 16, v6
	v_add3_u32 v19, v79, v19, s63
	v_and_or_b32 v35, v19, vcc_lo, v6
	v_add_u32_e32 v6, s42, v50
	v_ashrrev_i32_e32 v64, 7, v6
	v_and_or_b32 v19, v6, s58, v61
	v_ashrrev_i32_e32 v65, 31, v64
	v_lshlrev_b64 v[64:65], 19, v[64:65]
	v_lshrrev_b32_e32 v6, 3, v19
	v_or_b32_e32 v6, v6, v45
	v_lshl_add_u64 v[64:65], s[40:41], 0, v[64:65]
	v_lshl_or_b32 v66, v6, 10, v62
	v_mov_b32_e32 v67, v8
	v_lshl_add_u64 v[64:65], v[64:65], 0, s[34:35]
	v_lshl_add_u64 v[64:65], v[64:65], 0, v[66:67]
	global_store_dwordx4 v[64:65], v[32:35], off
	s_waitcnt lgkmcnt(0)
	s_cbranch_scc1 .LBB0_29

.LBB0_35:
	s_lshl_b32 s47, s45, 1
	s_lshl_b32 s52, s35, 1
	v_add_u32_e32 v66, s47, v4
	v_add_u32_e32 v64, s52, v17
	v_add_u32_e32 v68, s52, v19
	v_add_u32_e32 v70, s47, v6
	v_add_u32_e32 v72, s52, v21
	v_add_u32_e32 v74, s47, v36
	v_add_u32_e32 v76, s52, v23
	v_add_u32_e32 v78, s47, v38
	v_add_u32_e32 v80, s52, v25
	v_add_u32_e32 v82, s47, v40
	v_add_u32_e32 v84, s52, v27
	v_add_u32_e32 v86, s47, v42
	v_add_u32_e32 v88, s52, v29
	v_add_u32_e32 v90, s47, v44
	v_add_u32_e32 v92, s52, v31
	v_add_u32_e32 v94, s47, v46
	v_ashrrev_i32_e32 v67, 31, v66
	v_ashrrev_i32_e32 v65, 31, v64
	v_ashrrev_i32_e32 v71, 31, v70
	v_ashrrev_i32_e32 v69, 31, v68
	v_ashrrev_i32_e32 v75, 31, v74
	v_ashrrev_i32_e32 v73, 31, v72
	v_ashrrev_i32_e32 v79, 31, v78
	v_ashrrev_i32_e32 v77, 31, v76
	v_ashrrev_i32_e32 v83, 31, v82
	v_ashrrev_i32_e32 v81, 31, v80
	v_ashrrev_i32_e32 v87, 31, v86
	v_ashrrev_i32_e32 v85, 31, v84
	v_ashrrev_i32_e32 v91, 31, v90
	v_ashrrev_i32_e32 v89, 31, v88
	v_ashrrev_i32_e32 v95, 31, v94
	v_ashrrev_i32_e32 v93, 31, v92
	v_lshlrev_b64 v[66:67], 13, v[66:67]
	v_lshlrev_b64 v[64:65], 13, v[64:65]
	v_lshlrev_b64 v[68:69], 13, v[68:69]
	v_lshlrev_b64 v[70:71], 13, v[70:71]
	v_lshlrev_b64 v[72:73], 13, v[72:73]
	v_lshlrev_b64 v[74:75], 13, v[74:75]
	v_lshlrev_b64 v[76:77], 13, v[76:77]
	v_lshlrev_b64 v[78:79], 13, v[78:79]
	v_lshlrev_b64 v[80:81], 13, v[80:81]
	v_lshlrev_b64 v[82:83], 13, v[82:83]
	v_lshlrev_b64 v[84:85], 13, v[84:85]
	v_lshlrev_b64 v[86:87], 13, v[86:87]
	v_lshlrev_b64 v[88:89], 13, v[88:89]
	v_lshlrev_b64 v[90:91], 13, v[90:91]
	v_lshlrev_b64 v[92:93], 13, v[92:93]
	v_lshlrev_b64 v[94:95], 13, v[94:95]
	v_lshl_add_u64 v[66:67], v[34:35], 0, v[66:67]
	v_lshl_add_u64 v[64:65], v[34:35], 0, v[64:65]
	v_lshl_add_u64 v[70:71], v[34:35], 0, v[70:71]
	v_lshl_add_u64 v[68:69], v[34:35], 0, v[68:69]
	v_lshl_add_u64 v[74:75], v[34:35], 0, v[74:75]
	v_lshl_add_u64 v[72:73], v[34:35], 0, v[72:73]
	v_lshl_add_u64 v[78:79], v[34:35], 0, v[78:79]
	v_lshl_add_u64 v[76:77], v[34:35], 0, v[76:77]
	v_lshl_add_u64 v[82:83], v[34:35], 0, v[82:83]
	v_lshl_add_u64 v[80:81], v[34:35], 0, v[80:81]
	v_lshl_add_u64 v[86:87], v[34:35], 0, v[86:87]
	v_lshl_add_u64 v[84:85], v[34:35], 0, v[84:85]
	v_lshl_add_u64 v[90:91], v[34:35], 0, v[90:91]
	v_lshl_add_u64 v[88:89], v[34:35], 0, v[88:89]
	v_lshl_add_u64 v[94:95], v[34:35], 0, v[94:95]
	v_lshl_add_u64 v[92:93], v[34:35], 0, v[92:93]
	global_load_dword v63, v[66:67], off nt
	global_load_dword v96, v[64:65], off nt
	global_load_dword v97, v[70:71], off nt
	global_load_dword v98, v[68:69], off nt
	global_load_dword v99, v[74:75], off nt
	global_load_dword v100, v[72:73], off nt
	global_load_dword v101, v[78:79], off nt
	global_load_dword v102, v[76:77], off nt
	global_load_dword v103, v[82:83], off nt
	global_load_dword v104, v[80:81], off nt
	global_load_dword v105, v[86:87], off nt
	global_load_dword v106, v[84:85], off nt
	global_load_dword v107, v[90:91], off nt
	global_load_dword v108, v[88:89], off nt
	global_load_dword v109, v[94:95], off nt
	global_load_dword v110, v[92:93], off nt
	s_add_i32 s45, s45, 16
	s_add_i32 s35, s35, 16
	s_add_i32 s46, s46, -16
	v_add_u32_e32 v64, s47, v12
	v_add_u32_e32 v66, s52, v1
	v_add_u32_e32 v70, s52, v3
	v_add_u32_e32 v68, s47, v14
	v_add_u32_e32 v74, s52, v5
	v_add_u32_e32 v72, s47, v16
	v_add_u32_e32 v78, s52, v7
	v_add_u32_e32 v76, s47, v18
	v_add_u32_e32 v82, s52, v9
	v_add_u32_e32 v80, s47, v20
	v_add_u32_e32 v86, s52, v11
	v_add_u32_e32 v84, s47, v22
	v_add_u32_e32 v90, s52, v13
	v_add_u32_e32 v88, s47, v24
	v_add_u32_e32 v94, s52, v15
	v_add_u32_e32 v92, s47, v26
	s_cmp_lg_u32 s46, 0
	v_mad_u64_u32 v[64:65], s[52:53], v64, s62, v[2:3]
	v_mad_u64_u32 v[66:67], s[52:53], v66, s62, v[2:3]
	v_mad_u64_u32 v[68:69], s[52:53], v68, s62, v[2:3]
	v_mad_u64_u32 v[70:71], s[52:53], v70, s62, v[2:3]
	v_mad_u64_u32 v[72:73], s[52:53], v72, s62, v[2:3]
	v_mad_u64_u32 v[74:75], s[52:53], v74, s62, v[2:3]
	v_mad_u64_u32 v[76:77], s[52:53], v76, s62, v[2:3]
	v_mad_u64_u32 v[78:79], s[52:53], v78, s62, v[2:3]
	v_mad_u64_u32 v[80:81], s[52:53], v80, s62, v[2:3]
	v_mad_u64_u32 v[82:83], s[52:53], v82, s62, v[2:3]
	v_mad_u64_u32 v[84:85], s[52:53], v84, s62, v[2:3]
	v_mad_u64_u32 v[86:87], s[52:53], v86, s62, v[2:3]
	v_mad_u64_u32 v[88:89], s[52:53], v88, s62, v[2:3]
	v_mad_u64_u32 v[90:91], s[52:53], v90, s62, v[2:3]
	v_mad_u64_u32 v[92:93], s[52:53], v92, s62, v[2:3]
	v_mad_u64_u32 v[94:95], s[52:53], v94, s62, v[2:3]
	s_waitcnt vmcnt(0)
	ds_write_b32 v64, v63
	s_waitcnt vmcnt(14)
	ds_write_b32 v66, v96
	s_waitcnt vmcnt(13)
	ds_write_b32 v68, v97
	s_waitcnt vmcnt(12)
	ds_write_b32 v70, v98
	s_waitcnt vmcnt(11)
	ds_write_b32 v72, v99
	s_waitcnt vmcnt(10)
	ds_write_b32 v74, v100
	s_waitcnt vmcnt(9)
	ds_write_b32 v76, v101
	s_waitcnt vmcnt(8)
	ds_write_b32 v78, v102
	s_waitcnt vmcnt(7)
	ds_write_b32 v80, v103
	s_waitcnt vmcnt(6)
	ds_write_b32 v82, v104
	s_waitcnt vmcnt(5)
	ds_write_b32 v84, v105
	s_waitcnt vmcnt(4)
	ds_write_b32 v86, v106
	s_waitcnt vmcnt(3)
	ds_write_b32 v88, v107
	s_waitcnt vmcnt(2)
	ds_write_b32 v90, v108
	s_waitcnt vmcnt(1)
	ds_write_b32 v92, v109
	s_waitcnt vmcnt(0)
	ds_write_b32 v94, v110
	s_cbranch_scc1 .LBB0_35
	s_waitcnt lgkmcnt(0)
	ds_read2_b32 v[34:35], v37 offset1:8
	ds_read2_b32 v[68:69], v37 offset0:33 offset1:41
	ds_read2_b32 v[70:71], v37 offset0:66 offset1:74
	ds_read2_b32 v[72:73], v37 offset0:99 offset1:107
	ds_read2_b32 v[74:75], v37 offset0:132 offset1:140
	s_waitcnt lgkmcnt(4)
	v_bfe_u32 v6, v34, 16, 1
	v_add3_u32 v6, v34, v6, s63
	s_waitcnt lgkmcnt(3)
	v_bfe_u32 v17, v68, 16, 1
	v_lshrrev_b32_e32 v6, 16, v6
	v_add3_u32 v17, v68, v17, s63
	ds_read2_b32 v[76:77], v37 offset0:165 offset1:173
	v_and_or_b32 v64, v17, vcc_lo, v6
	s_waitcnt lgkmcnt(3)
	v_bfe_u32 v6, v70, 16, 1
	v_add3_u32 v6, v70, v6, s63
	s_waitcnt lgkmcnt(2)
	v_bfe_u32 v17, v72, 16, 1
	ds_read2_b32 v[78:79], v37 offset0:198 offset1:206
	v_lshrrev_b32_e32 v6, 16, v6
	v_add3_u32 v17, v72, v17, s63
	ds_read2_b32 v[80:81], v37 offset0:231 offset1:239
	v_and_or_b32 v65, v17, vcc_lo, v6
	s_waitcnt lgkmcnt(3)
	v_bfe_u32 v6, v74, 16, 1
	v_add3_u32 v6, v74, v6, s63
	s_waitcnt lgkmcnt(2)
	v_bfe_u32 v17, v76, 16, 1
	v_lshrrev_b32_e32 v6, 16, v6
	v_add3_u32 v17, v76, v17, s63
	v_and_or_b32 v66, v17, vcc_lo, v6
	s_waitcnt lgkmcnt(1)
	v_bfe_u32 v6, v78, 16, 1
	v_add3_u32 v6, v78, v6, s63
	s_waitcnt lgkmcnt(0)
	v_bfe_u32 v17, v80, 16, 1
	v_add_u32_e32 v4, s44, v43
	v_lshrrev_b32_e32 v6, 16, v6
	v_add3_u32 v17, v80, v17, s63
	s_addk_i32 s34, 0xc00
	v_and_or_b32 v67, v17, vcc_lo, v6
	v_and_or_b32 v6, v4, s58, v39
	v_ashrrev_i32_e32 v82, 7, v4
	s_ashr_i32 s34, s34, 6
	v_ashrrev_i32_e32 v83, 31, v82
	v_lshrrev_b32_e32 v4, 3, v6
	s_ashr_i32 s35, s34, 31
	v_lshlrev_b64 v[82:83], 20, v[82:83]
	v_or_b32_e32 v4, v4, v45
	s_lshl_b64 s[34:35], s[34:35], 14
	v_lshl_or_b32 v84, v4, 10, v41
	v_lshl_add_u64 v[82:83], s[40:41], 0, v[82:83]
	v_bfe_u32 v4, v35, 16, 1
	v_mov_b32_e32 v85, v8
	v_lshl_add_u64 v[82:83], v[82:83], 0, s[34:35]
	v_add3_u32 v4, v35, v4, s63
	v_bfe_u32 v6, v69, 16, 1
	v_lshl_add_u64 v[82:83], v[82:83], 0, v[84:85]
	v_lshrrev_b32_e32 v4, 16, v4
	v_add3_u32 v6, v69, v6, s63
	global_store_dwordx4 v[82:83], v[64:67], off
	v_mov_b32_e32 v69, v8
	s_add_i32 s25, s25, s22
	v_and_or_b32 v64, v6, vcc_lo, v4
	v_bfe_u32 v4, v71, 16, 1
	v_add3_u32 v4, v71, v4, s63
	v_bfe_u32 v6, v73, 16, 1
	v_lshrrev_b32_e32 v4, 16, v4
	v_add3_u32 v6, v73, v6, s63
	v_and_or_b32 v65, v6, vcc_lo, v4
	v_bfe_u32 v4, v75, 16, 1
	v_add3_u32 v4, v75, v4, s63
	v_bfe_u32 v6, v77, 16, 1
	v_lshrrev_b32_e32 v4, 16, v4
	v_add3_u32 v6, v77, v6, s63
	v_and_or_b32 v66, v6, vcc_lo, v4
	v_bfe_u32 v4, v79, 16, 1
	v_add3_u32 v4, v79, v4, s63
	v_bfe_u32 v6, v81, 16, 1
	v_lshrrev_b32_e32 v4, 16, v4
	v_add3_u32 v6, v81, v6, s63
	v_and_or_b32 v67, v6, vcc_lo, v4
	v_add_u32_e32 v4, s44, v47
	v_ashrrev_i32_e32 v34, 7, v4
	v_and_or_b32 v6, v4, s58, v48
	v_ashrrev_i32_e32 v35, 31, v34
	v_lshlrev_b64 v[34:35], 20, v[34:35]
	v_lshrrev_b32_e32 v4, 3, v6
	v_or_b32_e32 v4, v4, v45
	v_lshl_add_u64 v[34:35], s[40:41], 0, v[34:35]
	v_lshl_or_b32 v68, v4, 10, v58
	v_lshl_add_u64 v[34:35], v[34:35], 0, s[34:35]
	ds_read2_b32 v[70:71], v37 offset0:16 offset1:24
	v_lshl_add_u64 v[34:35], v[34:35], 0, v[68:69]
	global_store_dwordx4 v[34:35], v[64:67], off
	ds_read2_b32 v[34:35], v37 offset0:49 offset1:57
	ds_read2_b32 v[68:69], v37 offset0:82 offset1:90
	ds_read2_b32 v[72:73], v37 offset0:115 offset1:123
	s_waitcnt lgkmcnt(3)
	v_bfe_u32 v4, v70, 16, 1
	v_add3_u32 v4, v70, v4, s63
	s_waitcnt lgkmcnt(2)
	v_bfe_u32 v6, v34, 16, 1
	ds_read2_b32 v[74:75], v37 offset0:148 offset1:156
	v_lshrrev_b32_e32 v4, 16, v4
	v_add3_u32 v6, v34, v6, s63
	ds_read2_b32 v[76:77], v37 offset0:181 offset1:189
	v_and_or_b32 v64, v6, vcc_lo, v4
	s_waitcnt lgkmcnt(3)
	v_bfe_u32 v4, v68, 16, 1
	v_add3_u32 v4, v68, v4, s63
	s_waitcnt lgkmcnt(2)
	v_bfe_u32 v6, v72, 16, 1
	ds_read2_b32 v[78:79], v37 offset0:214 offset1:222
	v_lshrrev_b32_e32 v4, 16, v4
	v_add3_u32 v6, v72, v6, s63
	ds_read2_b32 v[80:81], v37 offset0:247 offset1:255
	v_and_or_b32 v65, v6, vcc_lo, v4
	s_waitcnt lgkmcnt(3)
	v_bfe_u32 v4, v74, 16, 1
	v_add3_u32 v4, v74, v4, s63
	s_waitcnt lgkmcnt(2)
	v_bfe_u32 v6, v76, 16, 1
	v_lshrrev_b32_e32 v4, 16, v4
	v_add3_u32 v6, v76, v6, s63
	v_and_or_b32 v66, v6, vcc_lo, v4
	s_waitcnt lgkmcnt(1)
	v_bfe_u32 v4, v78, 16, 1
	v_add3_u32 v4, v78, v4, s63
	s_waitcnt lgkmcnt(0)
	v_bfe_u32 v6, v80, 16, 1
	v_lshrrev_b32_e32 v4, 16, v4
	v_add3_u32 v6, v80, v6, s63
	v_and_or_b32 v67, v6, vcc_lo, v4
	v_add_u32_e32 v4, s44, v49
	v_and_or_b32 v6, v4, s58, v59
	v_ashrrev_i32_e32 v82, 7, v4
	v_ashrrev_i32_e32 v83, 31, v82
	v_lshrrev_b32_e32 v4, 3, v6
	v_lshlrev_b64 v[82:83], 20, v[82:83]
	v_or_b32_e32 v4, v4, v45
	v_lshl_or_b32 v84, v4, 10, v60
	v_lshl_add_u64 v[82:83], s[40:41], 0, v[82:83]
	v_bfe_u32 v4, v71, 16, 1
	v_lshl_add_u64 v[82:83], v[82:83], 0, s[34:35]
	v_add3_u32 v4, v71, v4, s63
	v_bfe_u32 v6, v35, 16, 1
	v_lshl_add_u64 v[82:83], v[82:83], 0, v[84:85]
	v_lshrrev_b32_e32 v4, 16, v4
	v_add3_u32 v6, v35, v6, s63
	global_store_dwordx4 v[82:83], v[64:67], off
	s_cmpk_lt_i32 s25, 0x400
	s_nop 0
	v_and_or_b32 v64, v6, vcc_lo, v4
	v_bfe_u32 v4, v69, 16, 1
	v_add3_u32 v4, v69, v4, s63
	v_bfe_u32 v6, v73, 16, 1
	v_lshrrev_b32_e32 v4, 16, v4
	v_add3_u32 v6, v73, v6, s63
	v_and_or_b32 v65, v6, vcc_lo, v4
	v_bfe_u32 v4, v75, 16, 1
	v_add3_u32 v4, v75, v4, s63
	v_bfe_u32 v6, v77, 16, 1
	v_lshrrev_b32_e32 v4, 16, v4
	v_add3_u32 v6, v77, v6, s63
	v_and_or_b32 v66, v6, vcc_lo, v4
	v_bfe_u32 v4, v79, 16, 1
	v_add3_u32 v4, v79, v4, s63
	v_bfe_u32 v6, v81, 16, 1
	v_lshrrev_b32_e32 v4, 16, v4
	v_add3_u32 v6, v81, v6, s63
	v_and_or_b32 v67, v6, vcc_lo, v4
	v_add_u32_e32 v4, s44, v50
	v_ashrrev_i32_e32 v34, 7, v4
	v_and_or_b32 v6, v4, s58, v61
	v_ashrrev_i32_e32 v35, 31, v34
	v_lshlrev_b64 v[34:35], 20, v[34:35]
	v_lshrrev_b32_e32 v4, 3, v6
	v_or_b32_e32 v4, v4, v45
	v_lshl_add_u64 v[34:35], s[40:41], 0, v[34:35]
	v_lshl_or_b32 v68, v4, 10, v62
	v_mov_b32_e32 v69, v8
	v_lshl_add_u64 v[34:35], v[34:35], 0, s[34:35]
	v_lshl_add_u64 v[34:35], v[34:35], 0, v[68:69]
	global_store_dwordx4 v[34:35], v[64:67], off
	s_waitcnt lgkmcnt(0)
	s_cbranch_scc1 .LBB0_34
	s_load_dwordx2 s[34:35], s[10:11], 0x70
	s_lshl_b64 s[42:43], s[42:43], 2
	v_lshlrev_b32_e32 v32, 2, v28
	v_mov_b32_e32 v33, v8
	s_mov_b32 s25, s51
	s_waitcnt lgkmcnt(0)
	s_add_u32 s34, s34, s42
	s_addc_u32 s35, s35, s43
	v_lshl_add_u64 v[32:33], s[34:35], 0, v[32:33]

.LBB0_39:
	s_lshl_b32 s45, s43, 1
	s_lshl_b32 s46, s35, 1
	v_add_u32_e32 v66, s45, v4
	v_add_u32_e32 v64, s46, v17
	v_add_u32_e32 v68, s46, v19
	v_add_u32_e32 v70, s45, v6
	v_add_u32_e32 v72, s46, v21
	v_add_u32_e32 v74, s45, v36
	v_add_u32_e32 v76, s46, v23
	v_add_u32_e32 v78, s45, v38
	v_add_u32_e32 v80, s46, v25
	v_add_u32_e32 v82, s45, v40
	v_add_u32_e32 v84, s46, v27
	v_add_u32_e32 v86, s45, v42
	v_add_u32_e32 v88, s46, v29
	v_add_u32_e32 v90, s45, v44
	v_add_u32_e32 v92, s46, v31
	v_add_u32_e32 v94, s45, v46
	v_ashrrev_i32_e32 v67, 31, v66
	v_ashrrev_i32_e32 v65, 31, v64
	v_ashrrev_i32_e32 v71, 31, v70
	v_ashrrev_i32_e32 v69, 31, v68
	v_ashrrev_i32_e32 v75, 31, v74
	v_ashrrev_i32_e32 v73, 31, v72
	v_ashrrev_i32_e32 v79, 31, v78
	v_ashrrev_i32_e32 v77, 31, v76
	v_ashrrev_i32_e32 v83, 31, v82
	v_ashrrev_i32_e32 v81, 31, v80
	v_ashrrev_i32_e32 v87, 31, v86
	v_ashrrev_i32_e32 v85, 31, v84
	v_ashrrev_i32_e32 v91, 31, v90
	v_ashrrev_i32_e32 v89, 31, v88
	v_ashrrev_i32_e32 v95, 31, v94
	v_ashrrev_i32_e32 v93, 31, v92
	v_lshlrev_b64 v[66:67], 13, v[66:67]
	v_lshlrev_b64 v[64:65], 13, v[64:65]
	v_lshlrev_b64 v[68:69], 13, v[68:69]
	v_lshlrev_b64 v[70:71], 13, v[70:71]
	v_lshlrev_b64 v[72:73], 13, v[72:73]
	v_lshlrev_b64 v[74:75], 13, v[74:75]
	v_lshlrev_b64 v[76:77], 13, v[76:77]
	v_lshlrev_b64 v[78:79], 13, v[78:79]
	v_lshlrev_b64 v[80:81], 13, v[80:81]
	v_lshlrev_b64 v[82:83], 13, v[82:83]
	v_lshlrev_b64 v[84:85], 13, v[84:85]
	v_lshlrev_b64 v[86:87], 13, v[86:87]
	v_lshlrev_b64 v[88:89], 13, v[88:89]
	v_lshlrev_b64 v[90:91], 13, v[90:91]
	v_lshlrev_b64 v[92:93], 13, v[92:93]
	v_lshlrev_b64 v[94:95], 13, v[94:95]
	v_lshl_add_u64 v[66:67], v[34:35], 0, v[66:67]
	v_lshl_add_u64 v[64:65], v[34:35], 0, v[64:65]
	v_lshl_add_u64 v[70:71], v[34:35], 0, v[70:71]
	v_lshl_add_u64 v[68:69], v[34:35], 0, v[68:69]
	v_lshl_add_u64 v[74:75], v[34:35], 0, v[74:75]
	v_lshl_add_u64 v[72:73], v[34:35], 0, v[72:73]
	v_lshl_add_u64 v[78:79], v[34:35], 0, v[78:79]
	v_lshl_add_u64 v[76:77], v[34:35], 0, v[76:77]
	v_lshl_add_u64 v[82:83], v[34:35], 0, v[82:83]
	v_lshl_add_u64 v[80:81], v[34:35], 0, v[80:81]
	v_lshl_add_u64 v[86:87], v[34:35], 0, v[86:87]
	v_lshl_add_u64 v[84:85], v[34:35], 0, v[84:85]
	v_lshl_add_u64 v[90:91], v[34:35], 0, v[90:91]
	v_lshl_add_u64 v[88:89], v[34:35], 0, v[88:89]
	v_lshl_add_u64 v[94:95], v[34:35], 0, v[94:95]
	v_lshl_add_u64 v[92:93], v[34:35], 0, v[92:93]
	global_load_dword v63, v[66:67], off nt
	global_load_dword v96, v[64:65], off nt
	global_load_dword v97, v[70:71], off nt
	global_load_dword v98, v[68:69], off nt
	global_load_dword v99, v[74:75], off nt
	global_load_dword v100, v[72:73], off nt
	global_load_dword v101, v[78:79], off nt
	global_load_dword v102, v[76:77], off nt
	global_load_dword v103, v[82:83], off nt
	global_load_dword v104, v[80:81], off nt
	global_load_dword v105, v[86:87], off nt
	global_load_dword v106, v[84:85], off nt
	global_load_dword v107, v[90:91], off nt
	global_load_dword v108, v[88:89], off nt
	global_load_dword v109, v[94:95], off nt
	global_load_dword v110, v[92:93], off nt
	s_add_i32 s43, s43, 16
	s_add_i32 s35, s35, 16
	s_add_i32 s44, s44, -16
	v_add_u32_e32 v64, s45, v12
	v_add_u32_e32 v66, s46, v1
	v_add_u32_e32 v70, s46, v3
	v_add_u32_e32 v68, s45, v14
	v_add_u32_e32 v74, s46, v5
	v_add_u32_e32 v72, s45, v16
	v_add_u32_e32 v78, s46, v7
	v_add_u32_e32 v76, s45, v18
	v_add_u32_e32 v82, s46, v9
	v_add_u32_e32 v80, s45, v20
	v_add_u32_e32 v86, s46, v11
	v_add_u32_e32 v84, s45, v22
	v_add_u32_e32 v90, s46, v13
	v_add_u32_e32 v88, s45, v24
	v_add_u32_e32 v94, s46, v15
	v_add_u32_e32 v92, s45, v26
	s_cmp_lg_u32 s44, 0
	v_mad_u64_u32 v[64:65], s[46:47], v64, s62, v[2:3]
	v_mad_u64_u32 v[66:67], s[46:47], v66, s62, v[2:3]
	v_mad_u64_u32 v[68:69], s[46:47], v68, s62, v[2:3]
	v_mad_u64_u32 v[70:71], s[46:47], v70, s62, v[2:3]
	v_mad_u64_u32 v[72:73], s[46:47], v72, s62, v[2:3]
	v_mad_u64_u32 v[74:75], s[46:47], v74, s62, v[2:3]
	v_mad_u64_u32 v[76:77], s[46:47], v76, s62, v[2:3]
	v_mad_u64_u32 v[78:79], s[46:47], v78, s62, v[2:3]
	v_mad_u64_u32 v[80:81], s[46:47], v80, s62, v[2:3]
	v_mad_u64_u32 v[82:83], s[46:47], v82, s62, v[2:3]
	v_mad_u64_u32 v[84:85], s[46:47], v84, s62, v[2:3]
	v_mad_u64_u32 v[86:87], s[46:47], v86, s62, v[2:3]
	v_mad_u64_u32 v[88:89], s[46:47], v88, s62, v[2:3]
	v_mad_u64_u32 v[90:91], s[46:47], v90, s62, v[2:3]
	v_mad_u64_u32 v[92:93], s[46:47], v92, s62, v[2:3]
	v_mad_u64_u32 v[94:95], s[46:47], v94, s62, v[2:3]
	s_waitcnt vmcnt(15)
	ds_write_b32 v64, v63
	s_waitcnt vmcnt(14)
	ds_write_b32 v66, v96
	s_waitcnt vmcnt(13)
	ds_write_b32 v68, v97
	s_waitcnt vmcnt(12)
	ds_write_b32 v70, v98
	s_waitcnt vmcnt(11)
	ds_write_b32 v72, v99
	s_waitcnt vmcnt(10)
	ds_write_b32 v74, v100
	s_waitcnt vmcnt(9)
	ds_write_b32 v76, v101
	s_waitcnt vmcnt(8)
	ds_write_b32 v78, v102
	s_waitcnt vmcnt(7)
	ds_write_b32 v80, v103
	s_waitcnt vmcnt(6)
	ds_write_b32 v82, v104
	s_waitcnt vmcnt(5)
	ds_write_b32 v84, v105
	s_waitcnt vmcnt(4)
	ds_write_b32 v86, v106
	s_waitcnt vmcnt(3)
	ds_write_b32 v88, v107
	s_waitcnt vmcnt(2)
	ds_write_b32 v90, v108
	s_waitcnt vmcnt(1)
	ds_write_b32 v92, v109
	s_waitcnt vmcnt(0)
	ds_write_b32 v94, v110
	s_cbranch_scc1 .LBB0_39
	s_waitcnt lgkmcnt(0)
	ds_read2_b32 v[34:35], v37 offset1:8
	ds_read2_b32 v[68:69], v37 offset0:33 offset1:41
	ds_read2_b32 v[70:71], v37 offset0:66 offset1:74
	ds_read2_b32 v[72:73], v37 offset0:99 offset1:107
	ds_read2_b32 v[74:75], v37 offset0:132 offset1:140
	s_waitcnt lgkmcnt(4)
	v_bfe_u32 v6, v34, 16, 1
	v_add3_u32 v6, v34, v6, s63
	s_waitcnt lgkmcnt(3)
	v_bfe_u32 v17, v68, 16, 1
	v_lshrrev_b32_e32 v6, 16, v6
	v_add3_u32 v17, v68, v17, s63
	ds_read2_b32 v[76:77], v37 offset0:165 offset1:173
	v_and_or_b32 v64, v17, vcc_lo, v6
	s_waitcnt lgkmcnt(3)
	v_bfe_u32 v6, v70, 16, 1
	v_add3_u32 v6, v70, v6, s63
	s_waitcnt lgkmcnt(2)
	v_bfe_u32 v17, v72, 16, 1
	ds_read2_b32 v[78:79], v37 offset0:198 offset1:206
	v_lshrrev_b32_e32 v6, 16, v6
	v_add3_u32 v17, v72, v17, s63
	ds_read2_b32 v[80:81], v37 offset0:231 offset1:239
	v_and_or_b32 v65, v17, vcc_lo, v6
	s_waitcnt lgkmcnt(3)
	v_bfe_u32 v6, v74, 16, 1
	v_add3_u32 v6, v74, v6, s63
	s_waitcnt lgkmcnt(2)
	v_bfe_u32 v17, v76, 16, 1
	v_lshrrev_b32_e32 v6, 16, v6
	v_add3_u32 v17, v76, v17, s63
	v_and_or_b32 v66, v17, vcc_lo, v6
	s_waitcnt lgkmcnt(1)
	v_bfe_u32 v6, v78, 16, 1
	v_add3_u32 v6, v78, v6, s63
	s_waitcnt lgkmcnt(0)
	v_bfe_u32 v17, v80, 16, 1
	v_add_u32_e32 v4, s42, v43
	v_lshrrev_b32_e32 v6, 16, v6
	v_add3_u32 v17, v80, v17, s63
	s_addk_i32 s34, 0x800
	v_and_or_b32 v67, v17, vcc_lo, v6
	v_and_or_b32 v6, v4, s58, v39
	v_ashrrev_i32_e32 v82, 7, v4
	s_ashr_i32 s34, s34, 6
	v_ashrrev_i32_e32 v83, 31, v82
	v_lshrrev_b32_e32 v4, 3, v6
	s_ashr_i32 s35, s34, 31
	v_lshlrev_b64 v[82:83], 20, v[82:83]
	v_or_b32_e32 v4, v4, v45
	s_lshl_b64 s[34:35], s[34:35], 14
	v_lshl_or_b32 v84, v4, 10, v41
	v_lshl_add_u64 v[82:83], s[40:41], 0, v[82:83]
	v_bfe_u32 v4, v35, 16, 1
	v_mov_b32_e32 v85, v8
	v_lshl_add_u64 v[82:83], v[82:83], 0, s[34:35]
	v_add3_u32 v4, v35, v4, s63
	v_bfe_u32 v6, v69, 16, 1
	v_lshl_add_u64 v[82:83], v[82:83], 0, v[84:85]
	v_lshrrev_b32_e32 v4, 16, v4
	v_add3_u32 v6, v69, v6, s63
	global_store_dwordx4 v[82:83], v[64:67], off
	v_mov_b32_e32 v69, v8
	s_add_i32 s25, s25, s22
	v_and_or_b32 v64, v6, vcc_lo, v4
	v_bfe_u32 v4, v71, 16, 1
	v_add3_u32 v4, v71, v4, s63
	v_bfe_u32 v6, v73, 16, 1
	v_lshrrev_b32_e32 v4, 16, v4
	v_add3_u32 v6, v73, v6, s63
	v_and_or_b32 v65, v6, vcc_lo, v4
	v_bfe_u32 v4, v75, 16, 1
	v_add3_u32 v4, v75, v4, s63
	v_bfe_u32 v6, v77, 16, 1
	v_lshrrev_b32_e32 v4, 16, v4
	v_add3_u32 v6, v77, v6, s63
	v_and_or_b32 v66, v6, vcc_lo, v4
	v_bfe_u32 v4, v79, 16, 1
	v_add3_u32 v4, v79, v4, s63
	v_bfe_u32 v6, v81, 16, 1
	v_lshrrev_b32_e32 v4, 16, v4
	v_add3_u32 v6, v81, v6, s63
	v_and_or_b32 v67, v6, vcc_lo, v4
	v_add_u32_e32 v4, s42, v47
	v_ashrrev_i32_e32 v34, 7, v4
	v_and_or_b32 v6, v4, s58, v48
	v_ashrrev_i32_e32 v35, 31, v34
	v_lshlrev_b64 v[34:35], 20, v[34:35]
	v_lshrrev_b32_e32 v4, 3, v6
	v_or_b32_e32 v4, v4, v45
	v_lshl_add_u64 v[34:35], s[40:41], 0, v[34:35]
	v_lshl_or_b32 v68, v4, 10, v58
	v_lshl_add_u64 v[34:35], v[34:35], 0, s[34:35]
	ds_read2_b32 v[70:71], v37 offset0:16 offset1:24
	v_lshl_add_u64 v[34:35], v[34:35], 0, v[68:69]
	global_store_dwordx4 v[34:35], v[64:67], off
	ds_read2_b32 v[34:35], v37 offset0:49 offset1:57
	ds_read2_b32 v[68:69], v37 offset0:82 offset1:90
	ds_read2_b32 v[72:73], v37 offset0:115 offset1:123
	s_waitcnt lgkmcnt(3)
	v_bfe_u32 v4, v70, 16, 1
	v_add3_u32 v4, v70, v4, s63
	s_waitcnt lgkmcnt(2)
	v_bfe_u32 v6, v34, 16, 1
	ds_read2_b32 v[74:75], v37 offset0:148 offset1:156
	v_lshrrev_b32_e32 v4, 16, v4
	v_add3_u32 v6, v34, v6, s63
	ds_read2_b32 v[76:77], v37 offset0:181 offset1:189
	v_and_or_b32 v64, v6, vcc_lo, v4
	s_waitcnt lgkmcnt(3)
	v_bfe_u32 v4, v68, 16, 1
	v_add3_u32 v4, v68, v4, s63
	s_waitcnt lgkmcnt(2)
	v_bfe_u32 v6, v72, 16, 1
	ds_read2_b32 v[78:79], v37 offset0:214 offset1:222
	v_lshrrev_b32_e32 v4, 16, v4
	v_add3_u32 v6, v72, v6, s63
	ds_read2_b32 v[80:81], v37 offset0:247 offset1:255
	v_and_or_b32 v65, v6, vcc_lo, v4
	s_waitcnt lgkmcnt(3)
	v_bfe_u32 v4, v74, 16, 1
	v_add3_u32 v4, v74, v4, s63
	s_waitcnt lgkmcnt(2)
	v_bfe_u32 v6, v76, 16, 1
	v_lshrrev_b32_e32 v4, 16, v4
	v_add3_u32 v6, v76, v6, s63
	v_and_or_b32 v66, v6, vcc_lo, v4
	s_waitcnt lgkmcnt(1)
	v_bfe_u32 v4, v78, 16, 1
	v_add3_u32 v4, v78, v4, s63
	s_waitcnt lgkmcnt(0)
	v_bfe_u32 v6, v80, 16, 1
	v_lshrrev_b32_e32 v4, 16, v4
	v_add3_u32 v6, v80, v6, s63
	v_and_or_b32 v67, v6, vcc_lo, v4
	v_add_u32_e32 v4, s42, v49
	v_and_or_b32 v6, v4, s58, v59
	v_ashrrev_i32_e32 v82, 7, v4
	v_ashrrev_i32_e32 v83, 31, v82
	v_lshrrev_b32_e32 v4, 3, v6
	v_lshlrev_b64 v[82:83], 20, v[82:83]
	v_or_b32_e32 v4, v4, v45
	v_lshl_or_b32 v84, v4, 10, v60
	v_lshl_add_u64 v[82:83], s[40:41], 0, v[82:83]
	v_bfe_u32 v4, v71, 16, 1
	v_lshl_add_u64 v[82:83], v[82:83], 0, s[34:35]
	v_add3_u32 v4, v71, v4, s63
	v_bfe_u32 v6, v35, 16, 1
	v_lshl_add_u64 v[82:83], v[82:83], 0, v[84:85]
	v_lshrrev_b32_e32 v4, 16, v4
	v_add3_u32 v6, v35, v6, s63
	global_store_dwordx4 v[82:83], v[64:67], off
	s_cmpk_lt_i32 s25, 0x400
	s_nop 0
	v_and_or_b32 v64, v6, vcc_lo, v4
	v_bfe_u32 v4, v69, 16, 1
	v_add3_u32 v4, v69, v4, s63
	v_bfe_u32 v6, v73, 16, 1
	v_lshrrev_b32_e32 v4, 16, v4
	v_add3_u32 v6, v73, v6, s63
	v_and_or_b32 v65, v6, vcc_lo, v4
	v_bfe_u32 v4, v75, 16, 1
	v_add3_u32 v4, v75, v4, s63
	v_bfe_u32 v6, v77, 16, 1
	v_lshrrev_b32_e32 v4, 16, v4
	v_add3_u32 v6, v77, v6, s63
	v_and_or_b32 v66, v6, vcc_lo, v4
	v_bfe_u32 v4, v79, 16, 1
	v_add3_u32 v4, v79, v4, s63
	v_bfe_u32 v6, v81, 16, 1
	v_lshrrev_b32_e32 v4, 16, v4
	v_add3_u32 v6, v81, v6, s63
	v_and_or_b32 v67, v6, vcc_lo, v4
	v_add_u32_e32 v4, s42, v50
	v_ashrrev_i32_e32 v34, 7, v4
	v_and_or_b32 v6, v4, s58, v61
	v_ashrrev_i32_e32 v35, 31, v34
	v_lshlrev_b64 v[34:35], 20, v[34:35]
	v_lshrrev_b32_e32 v4, 3, v6
	v_or_b32_e32 v4, v4, v45
	v_lshl_add_u64 v[34:35], s[40:41], 0, v[34:35]
	v_lshl_or_b32 v68, v4, 10, v62
	v_mov_b32_e32 v69, v8
	v_lshl_add_u64 v[34:35], v[34:35], 0, s[34:35]
	v_lshl_add_u64 v[34:35], v[34:35], 0, v[68:69]
	global_store_dwordx4 v[34:35], v[64:67], off
	s_waitcnt lgkmcnt(0)
	s_cbranch_scc1 .LBB0_38

.LBB0_44:
	s_lshl_b32 s39, s35, 1
	s_lshl_b32 s42, s34, 1
	v_add_u32_e32 v66, s39, v6
	v_add_u32_e32 v64, s42, v19
	v_add_u32_e32 v68, s42, v21
	v_add_u32_e32 v70, s39, v34
	v_add_u32_e32 v72, s42, v23
	v_add_u32_e32 v74, s39, v36
	v_add_u32_e32 v76, s42, v25
	v_add_u32_e32 v78, s39, v38
	v_add_u32_e32 v80, s42, v27
	v_add_u32_e32 v82, s39, v40
	v_add_u32_e32 v84, s42, v29
	v_add_u32_e32 v86, s39, v42
	v_add_u32_e32 v88, s42, v31
	v_add_u32_e32 v90, s39, v44
	v_add_u32_e32 v92, s42, v35
	v_add_u32_e32 v94, s39, v46
	v_ashrrev_i32_e32 v67, 31, v66
	v_ashrrev_i32_e32 v65, 31, v64
	v_ashrrev_i32_e32 v71, 31, v70
	v_ashrrev_i32_e32 v69, 31, v68
	v_ashrrev_i32_e32 v75, 31, v74
	v_ashrrev_i32_e32 v73, 31, v72
	v_ashrrev_i32_e32 v79, 31, v78
	v_ashrrev_i32_e32 v77, 31, v76
	v_ashrrev_i32_e32 v83, 31, v82
	v_ashrrev_i32_e32 v81, 31, v80
	v_ashrrev_i32_e32 v87, 31, v86
	v_ashrrev_i32_e32 v85, 31, v84
	v_ashrrev_i32_e32 v91, 31, v90
	v_ashrrev_i32_e32 v89, 31, v88
	v_ashrrev_i32_e32 v95, 31, v94
	v_ashrrev_i32_e32 v93, 31, v92
	v_lshlrev_b64 v[66:67], 13, v[66:67]
	v_lshlrev_b64 v[64:65], 13, v[64:65]
	v_lshlrev_b64 v[68:69], 13, v[68:69]
	v_lshlrev_b64 v[70:71], 13, v[70:71]
	v_lshlrev_b64 v[72:73], 13, v[72:73]
	v_lshlrev_b64 v[74:75], 13, v[74:75]
	v_lshlrev_b64 v[76:77], 13, v[76:77]
	v_lshlrev_b64 v[78:79], 13, v[78:79]
	v_lshlrev_b64 v[80:81], 13, v[80:81]
	v_lshlrev_b64 v[82:83], 13, v[82:83]
	v_lshlrev_b64 v[84:85], 13, v[84:85]
	v_lshlrev_b64 v[86:87], 13, v[86:87]
	v_lshlrev_b64 v[88:89], 13, v[88:89]
	v_lshlrev_b64 v[90:91], 13, v[90:91]
	v_lshlrev_b64 v[92:93], 13, v[92:93]
	v_lshlrev_b64 v[94:95], 13, v[94:95]
	v_lshl_add_u64 v[66:67], v[32:33], 0, v[66:67]
	v_lshl_add_u64 v[64:65], v[32:33], 0, v[64:65]
	v_lshl_add_u64 v[70:71], v[32:33], 0, v[70:71]
	v_lshl_add_u64 v[68:69], v[32:33], 0, v[68:69]
	v_lshl_add_u64 v[74:75], v[32:33], 0, v[74:75]
	v_lshl_add_u64 v[72:73], v[32:33], 0, v[72:73]
	v_lshl_add_u64 v[78:79], v[32:33], 0, v[78:79]
	v_lshl_add_u64 v[76:77], v[32:33], 0, v[76:77]
	v_lshl_add_u64 v[82:83], v[32:33], 0, v[82:83]
	v_lshl_add_u64 v[80:81], v[32:33], 0, v[80:81]
	v_lshl_add_u64 v[86:87], v[32:33], 0, v[86:87]
	v_lshl_add_u64 v[84:85], v[32:33], 0, v[84:85]
	v_lshl_add_u64 v[90:91], v[32:33], 0, v[90:91]
	v_lshl_add_u64 v[88:89], v[32:33], 0, v[88:89]
	v_lshl_add_u64 v[94:95], v[32:33], 0, v[94:95]
	v_lshl_add_u64 v[92:93], v[32:33], 0, v[92:93]
	global_load_dword v63, v[66:67], off nt
	global_load_dword v96, v[64:65], off nt
	global_load_dword v97, v[70:71], off nt
	global_load_dword v98, v[68:69], off nt
	global_load_dword v99, v[74:75], off nt
	global_load_dword v100, v[72:73], off nt
	global_load_dword v101, v[78:79], off nt
	global_load_dword v102, v[76:77], off nt
	global_load_dword v103, v[82:83], off nt
	global_load_dword v104, v[80:81], off nt
	global_load_dword v105, v[86:87], off nt
	global_load_dword v106, v[84:85], off nt
	global_load_dword v107, v[90:91], off nt
	global_load_dword v108, v[88:89], off nt
	global_load_dword v109, v[94:95], off nt
	global_load_dword v110, v[92:93], off nt
	s_add_i32 s35, s35, 16
	s_add_i32 s34, s34, 16
	s_add_i32 s37, s37, -16
	v_add_u32_e32 v64, s39, v12
	v_add_u32_e32 v66, s42, v1
	v_add_u32_e32 v70, s42, v3
	v_add_u32_e32 v68, s39, v14
	v_add_u32_e32 v74, s42, v7
	v_add_u32_e32 v72, s39, v16
	v_add_u32_e32 v78, s42, v9
	v_add_u32_e32 v76, s39, v18
	v_add_u32_e32 v82, s42, v11
	v_add_u32_e32 v80, s39, v20
	v_add_u32_e32 v86, s42, v13
	v_add_u32_e32 v84, s39, v22
	v_add_u32_e32 v90, s42, v15
	v_add_u32_e32 v88, s39, v24
	v_add_u32_e32 v94, s42, v17
	v_add_u32_e32 v92, s39, v26
	s_cmp_lg_u32 s37, 0
	v_mad_u64_u32 v[64:65], s[42:43], v64, s62, v[2:3]
	v_mad_u64_u32 v[66:67], s[42:43], v66, s62, v[2:3]
	v_mad_u64_u32 v[68:69], s[42:43], v68, s62, v[2:3]
	v_mad_u64_u32 v[70:71], s[42:43], v70, s62, v[2:3]
	v_mad_u64_u32 v[72:73], s[42:43], v72, s62, v[2:3]
	v_mad_u64_u32 v[74:75], s[42:43], v74, s62, v[2:3]
	v_mad_u64_u32 v[76:77], s[42:43], v76, s62, v[2:3]
	v_mad_u64_u32 v[78:79], s[42:43], v78, s62, v[2:3]
	v_mad_u64_u32 v[80:81], s[42:43], v80, s62, v[2:3]
	v_mad_u64_u32 v[82:83], s[42:43], v82, s62, v[2:3]
	v_mad_u64_u32 v[84:85], s[42:43], v84, s62, v[2:3]
	v_mad_u64_u32 v[86:87], s[42:43], v86, s62, v[2:3]
	v_mad_u64_u32 v[88:89], s[42:43], v88, s62, v[2:3]
	v_mad_u64_u32 v[90:91], s[42:43], v90, s62, v[2:3]
	v_mad_u64_u32 v[92:93], s[42:43], v92, s62, v[2:3]
	v_mad_u64_u32 v[94:95], s[42:43], v94, s62, v[2:3]
	s_waitcnt vmcnt(0)
	ds_write_b32 v64, v63
	s_waitcnt vmcnt(14)
	ds_write_b32 v66, v96
	s_waitcnt vmcnt(13)
	ds_write_b32 v68, v97
	s_waitcnt vmcnt(12)
	ds_write_b32 v70, v98
	s_waitcnt vmcnt(11)
	ds_write_b32 v72, v99
	s_waitcnt vmcnt(10)
	ds_write_b32 v74, v100
	s_waitcnt vmcnt(9)
	ds_write_b32 v76, v101
	s_waitcnt vmcnt(8)
	ds_write_b32 v78, v102
	s_waitcnt vmcnt(7)
	ds_write_b32 v80, v103
	s_waitcnt vmcnt(6)
	ds_write_b32 v82, v104
	s_waitcnt vmcnt(5)
	ds_write_b32 v84, v105
	s_waitcnt vmcnt(4)
	ds_write_b32 v86, v106
	s_waitcnt vmcnt(3)
	ds_write_b32 v88, v107
	s_waitcnt vmcnt(2)
	ds_write_b32 v90, v108
	s_waitcnt vmcnt(1)
	ds_write_b32 v92, v109
	s_waitcnt vmcnt(0)
	ds_write_b32 v94, v110
	s_cbranch_scc1 .LBB0_44
	s_waitcnt lgkmcnt(0)
	ds_read2_b32 v[64:65], v37 offset1:8
	ds_read2_b32 v[66:67], v37 offset0:33 offset1:41
	ds_read2_b32 v[68:69], v37 offset0:66 offset1:74
	ds_read2_b32 v[70:71], v37 offset0:99 offset1:107
	ds_read2_b32 v[72:73], v37 offset0:132 offset1:140
	ds_read2_b32 v[74:75], v37 offset0:165 offset1:173
	s_waitcnt lgkmcnt(5)
	v_bfe_u32 v19, v64, 16, 1
	v_add3_u32 v19, v64, v19, s63
	s_waitcnt lgkmcnt(4)
	v_bfe_u32 v21, v66, 16, 1
	v_lshrrev_b32_e32 v19, 16, v19
	v_add3_u32 v21, v66, v21, s63
	v_and_or_b32 v32, v21, s45, v19
	s_waitcnt lgkmcnt(3)
	v_bfe_u32 v19, v68, 16, 1
	v_add3_u32 v19, v68, v19, s63
	s_waitcnt lgkmcnt(2)
	v_bfe_u32 v21, v70, 16, 1
	ds_read2_b32 v[76:77], v37 offset0:198 offset1:206
	v_lshrrev_b32_e32 v19, 16, v19
	v_add3_u32 v21, v70, v21, s63
	ds_read2_b32 v[78:79], v37 offset0:231 offset1:239
	v_and_or_b32 v33, v21, s45, v19
	s_waitcnt lgkmcnt(3)
	v_bfe_u32 v19, v72, 16, 1
	v_add3_u32 v19, v72, v19, s63
	s_waitcnt lgkmcnt(2)
	v_bfe_u32 v21, v74, 16, 1
	v_lshrrev_b32_e32 v19, 16, v19
	v_add3_u32 v21, v74, v21, s63
	v_and_or_b32 v34, v21, s45, v19
	s_waitcnt lgkmcnt(1)
	v_bfe_u32 v19, v76, 16, 1
	v_add3_u32 v19, v76, v19, s63
	s_waitcnt lgkmcnt(0)
	v_bfe_u32 v21, v78, 16, 1
	v_add_u32_e32 v6, s36, v43
	v_lshrrev_b32_e32 v19, 16, v19
	v_add3_u32 v21, v78, v21, s63
	v_and_or_b32 v35, v21, s45, v19
	v_and_or_b32 v19, v6, s44, v39
	v_ashrrev_i32_e32 v80, 7, v6
	v_ashrrev_i32_e32 v81, 31, v80
	v_lshrrev_b32_e32 v6, 3, v19
	s_ashr_i32 s39, s38, 31
	v_lshlrev_b64 v[80:81], 20, v[80:81]
	v_or_b32_e32 v6, v6, v45
	s_lshl_b64 s[34:35], s[38:39], 14
	v_lshl_or_b32 v82, v6, 10, v41
	v_lshl_add_u64 v[80:81], s[40:41], 0, v[80:81]
	v_bfe_u32 v6, v65, 16, 1
	v_mov_b32_e32 v83, v8
	v_lshl_add_u64 v[80:81], v[80:81], 0, s[34:35]
	v_add3_u32 v6, v65, v6, s63
	v_bfe_u32 v19, v67, 16, 1
	v_lshl_add_u64 v[80:81], v[80:81], 0, v[82:83]
	v_lshrrev_b32_e32 v6, 16, v6
	v_add3_u32 v19, v67, v19, s63
	global_store_dwordx4 v[80:81], v[32:35], off
	v_mov_b32_e32 v67, v8
	s_add_i32 s25, s25, s22
	v_and_or_b32 v32, v19, s45, v6
	v_bfe_u32 v6, v69, 16, 1
	v_add3_u32 v6, v69, v6, s63
	v_bfe_u32 v19, v71, 16, 1
	v_lshrrev_b32_e32 v6, 16, v6
	v_add3_u32 v19, v71, v19, s63
	v_and_or_b32 v33, v19, s45, v6
	v_bfe_u32 v6, v73, 16, 1
	v_add3_u32 v6, v73, v6, s63
	v_bfe_u32 v19, v75, 16, 1
	v_lshrrev_b32_e32 v6, 16, v6
	v_add3_u32 v19, v75, v19, s63
	v_and_or_b32 v34, v19, s45, v6
	v_bfe_u32 v6, v77, 16, 1
	v_add3_u32 v6, v77, v6, s63
	v_bfe_u32 v19, v79, 16, 1
	v_lshrrev_b32_e32 v6, 16, v6
	v_add3_u32 v19, v79, v19, s63
	v_and_or_b32 v35, v19, s45, v6
	v_add_u32_e32 v6, s36, v47
	v_ashrrev_i32_e32 v64, 7, v6
	v_and_or_b32 v19, v6, s44, v48
	v_ashrrev_i32_e32 v65, 31, v64
	v_lshlrev_b64 v[64:65], 20, v[64:65]
	v_lshrrev_b32_e32 v6, 3, v19
	v_or_b32_e32 v6, v6, v45
	v_lshl_add_u64 v[64:65], s[40:41], 0, v[64:65]
	v_lshl_or_b32 v66, v6, 10, v58
	v_lshl_add_u64 v[64:65], v[64:65], 0, s[34:35]
	ds_read2_b32 v[68:69], v37 offset0:16 offset1:24
	v_lshl_add_u64 v[64:65], v[64:65], 0, v[66:67]
	global_store_dwordx4 v[64:65], v[32:35], off
	ds_read2_b32 v[64:65], v37 offset0:49 offset1:57
	ds_read2_b32 v[66:67], v37 offset0:82 offset1:90
	ds_read2_b32 v[70:71], v37 offset0:115 offset1:123
	s_waitcnt lgkmcnt(3)
	v_bfe_u32 v6, v68, 16, 1
	v_add3_u32 v6, v68, v6, s63
	s_waitcnt lgkmcnt(2)
	v_bfe_u32 v19, v64, 16, 1
	ds_read2_b32 v[72:73], v37 offset0:148 offset1:156
	v_lshrrev_b32_e32 v6, 16, v6
	v_add3_u32 v19, v64, v19, s63
	ds_read2_b32 v[74:75], v37 offset0:181 offset1:189
	v_and_or_b32 v32, v19, s45, v6
	s_waitcnt lgkmcnt(3)
	v_bfe_u32 v6, v66, 16, 1
	v_add3_u32 v6, v66, v6, s63
	s_waitcnt lgkmcnt(2)
	v_bfe_u32 v19, v70, 16, 1
	ds_read2_b32 v[76:77], v37 offset0:214 offset1:222
	v_lshrrev_b32_e32 v6, 16, v6
	v_add3_u32 v19, v70, v19, s63
	ds_read2_b32 v[78:79], v37 offset0:247 offset1:255
	v_and_or_b32 v33, v19, s45, v6
	s_waitcnt lgkmcnt(3)
	v_bfe_u32 v6, v72, 16, 1
	v_add3_u32 v6, v72, v6, s63
	s_waitcnt lgkmcnt(2)
	v_bfe_u32 v19, v74, 16, 1
	v_lshrrev_b32_e32 v6, 16, v6
	v_add3_u32 v19, v74, v19, s63
	v_and_or_b32 v34, v19, s45, v6
	s_waitcnt lgkmcnt(1)
	v_bfe_u32 v6, v76, 16, 1
	v_add3_u32 v6, v76, v6, s63
	s_waitcnt lgkmcnt(0)
	v_bfe_u32 v19, v78, 16, 1
	v_lshrrev_b32_e32 v6, 16, v6
	v_add3_u32 v19, v78, v19, s63
	v_and_or_b32 v35, v19, s45, v6
	v_add_u32_e32 v6, s36, v49
	v_and_or_b32 v19, v6, s44, v59
	v_ashrrev_i32_e32 v80, 7, v6
	v_ashrrev_i32_e32 v81, 31, v80
	v_lshrrev_b32_e32 v6, 3, v19
	v_lshlrev_b64 v[80:81], 20, v[80:81]
	v_or_b32_e32 v6, v6, v45
	v_lshl_or_b32 v82, v6, 10, v60
	v_lshl_add_u64 v[80:81], s[40:41], 0, v[80:81]
	v_bfe_u32 v6, v69, 16, 1
	v_lshl_add_u64 v[80:81], v[80:81], 0, s[34:35]
	v_add3_u32 v6, v69, v6, s63
	v_bfe_u32 v19, v65, 16, 1
	v_lshl_add_u64 v[80:81], v[80:81], 0, v[82:83]
	v_lshrrev_b32_e32 v6, 16, v6
	v_add3_u32 v19, v65, v19, s63
	global_store_dwordx4 v[80:81], v[32:35], off
	s_cmpk_lt_i32 s25, 0x800
	s_nop 0
	v_and_or_b32 v32, v19, s45, v6
	v_bfe_u32 v6, v67, 16, 1
	v_add3_u32 v6, v67, v6, s63
	v_bfe_u32 v19, v71, 16, 1
	v_lshrrev_b32_e32 v6, 16, v6
	v_add3_u32 v19, v71, v19, s63
	v_and_or_b32 v33, v19, s45, v6
	v_bfe_u32 v6, v73, 16, 1
	v_add3_u32 v6, v73, v6, s63
	v_bfe_u32 v19, v75, 16, 1
	v_lshrrev_b32_e32 v6, 16, v6
	v_add3_u32 v19, v75, v19, s63
	v_and_or_b32 v34, v19, s45, v6
	v_bfe_u32 v6, v77, 16, 1
	v_add3_u32 v6, v77, v6, s63
	v_bfe_u32 v19, v79, 16, 1
	v_lshrrev_b32_e32 v6, 16, v6
	v_add3_u32 v19, v79, v19, s63
	v_and_or_b32 v35, v19, s45, v6
	v_add_u32_e32 v6, s36, v50
	v_ashrrev_i32_e32 v64, 7, v6
	v_and_or_b32 v19, v6, s44, v61
	v_ashrrev_i32_e32 v65, 31, v64
	v_lshlrev_b64 v[64:65], 20, v[64:65]
	v_lshrrev_b32_e32 v6, 3, v19
	v_or_b32_e32 v6, v6, v45
	v_lshl_add_u64 v[64:65], s[40:41], 0, v[64:65]
	v_lshl_or_b32 v66, v6, 10, v62
	v_mov_b32_e32 v67, v8
	v_lshl_add_u64 v[64:65], v[64:65], 0, s[34:35]
	v_lshl_add_u64 v[64:65], v[64:65], 0, v[66:67]
	global_store_dwordx4 v[64:65], v[32:35], off
	s_waitcnt lgkmcnt(0)
	s_cbranch_scc1 .LBB0_43

.LBB0_51:
	s_lshl_b32 s46, s41, 1
	s_lshl_b32 s47, s35, 1
	v_add_u32_e32 v65, s46, v2
	v_add_u32_e32 v41, s47, v3
	v_add_u32_e32 v72, s47, v5
	v_add_u32_e32 v70, s46, v4
	v_add_u32_e32 v76, s47, v7
	v_add_u32_e32 v74, s46, v6
	v_add_u32_e32 v80, s47, v25
	v_add_u32_e32 v78, s46, v40
	v_add_u32_e32 v84, s47, v27
	v_add_u32_e32 v82, s46, v42
	v_add_u32_e32 v88, s47, v29
	v_add_u32_e32 v86, s46, v44
	v_add_u32_e32 v92, s47, v31
	v_add_u32_e32 v90, s46, v46
	v_add_u32_e32 v96, s47, v33
	v_add_u32_e32 v94, s46, v48
	v_mad_i64_i32 v[66:67], s[44:45], v65, s26, v[0:1]
	v_mad_i64_i32 v[68:69], s[44:45], v41, s26, v[0:1]
	v_mad_i64_i32 v[70:71], s[44:45], v70, s26, v[0:1]
	v_mad_i64_i32 v[72:73], s[44:45], v72, s26, v[0:1]
	v_mad_i64_i32 v[74:75], s[44:45], v74, s26, v[0:1]
	v_mad_i64_i32 v[76:77], s[44:45], v76, s26, v[0:1]
	v_mad_i64_i32 v[78:79], s[44:45], v78, s26, v[0:1]
	v_mad_i64_i32 v[80:81], s[44:45], v80, s26, v[0:1]
	v_mad_i64_i32 v[82:83], s[44:45], v82, s26, v[0:1]
	v_mad_i64_i32 v[84:85], s[44:45], v84, s26, v[0:1]
	v_mad_i64_i32 v[86:87], s[44:45], v86, s26, v[0:1]
	v_mad_i64_i32 v[88:89], s[44:45], v88, s26, v[0:1]
	v_mad_i64_i32 v[90:91], s[44:45], v90, s26, v[0:1]
	v_mad_i64_i32 v[92:93], s[44:45], v92, s26, v[0:1]
	v_mad_i64_i32 v[94:95], s[44:45], v94, s26, v[0:1]
	v_mad_i64_i32 v[96:97], s[44:45], v96, s26, v[0:1]
	global_load_dword v41, v[66:67], off nt
	global_load_dword v65, v[68:69], off nt
	global_load_dword v98, v[70:71], off nt
	global_load_dword v99, v[72:73], off nt
	global_load_dword v100, v[74:75], off nt
	global_load_dword v101, v[76:77], off nt
	global_load_dword v102, v[78:79], off nt
	global_load_dword v103, v[80:81], off nt
	global_load_dword v104, v[82:83], off nt
	global_load_dword v105, v[84:85], off nt
	global_load_dword v106, v[86:87], off nt
	global_load_dword v107, v[88:89], off nt
	global_load_dword v108, v[90:91], off nt
	global_load_dword v109, v[92:93], off nt
	global_load_dword v110, v[94:95], off nt
	global_load_dword v111, v[96:97], off nt
	s_add_i32 s41, s41, 16
	s_add_i32 s35, s35, 16
	s_add_i32 s43, s43, -16
	v_add_u32_e32 v66, s46, v12
	v_add_u32_e32 v68, s47, v9
	v_add_u32_e32 v72, s47, v11
	v_add_u32_e32 v70, s46, v14
	v_add_u32_e32 v76, s47, v13
	v_add_u32_e32 v74, s46, v16
	v_add_u32_e32 v80, s47, v15
	v_add_u32_e32 v78, s46, v18
	v_add_u32_e32 v84, s47, v17
	v_add_u32_e32 v82, s46, v20
	v_add_u32_e32 v88, s47, v19
	v_add_u32_e32 v86, s46, v22
	v_add_u32_e32 v92, s47, v21
	v_add_u32_e32 v90, s46, v24
	v_add_u32_e32 v96, s47, v23
	v_add_u32_e32 v94, s46, v26
	s_cmp_lg_u32 s43, 0
	v_mad_u64_u32 v[66:67], s[44:45], v66, s62, v[32:33]
	v_mad_u64_u32 v[68:69], s[44:45], v68, s62, v[32:33]
	v_mad_u64_u32 v[70:71], s[44:45], v70, s62, v[32:33]
	v_mad_u64_u32 v[72:73], s[44:45], v72, s62, v[32:33]
	v_mad_u64_u32 v[74:75], s[44:45], v74, s62, v[32:33]
	v_mad_u64_u32 v[76:77], s[44:45], v76, s62, v[32:33]
	v_mad_u64_u32 v[78:79], s[44:45], v78, s62, v[32:33]
	v_mad_u64_u32 v[80:81], s[44:45], v80, s62, v[32:33]
	v_mad_u64_u32 v[82:83], s[44:45], v82, s62, v[32:33]
	v_mad_u64_u32 v[84:85], s[44:45], v84, s62, v[32:33]
	v_mad_u64_u32 v[86:87], s[44:45], v86, s62, v[32:33]
	v_mad_u64_u32 v[88:89], s[44:45], v88, s62, v[32:33]
	v_mad_u64_u32 v[90:91], s[44:45], v90, s62, v[32:33]
	v_mad_u64_u32 v[92:93], s[44:45], v92, s62, v[32:33]
	v_mad_u64_u32 v[94:95], s[44:45], v94, s62, v[32:33]
	v_mad_u64_u32 v[96:97], s[44:45], v96, s62, v[32:33]
	s_waitcnt vmcnt(0)
	ds_write_b32 v66, v41
	s_waitcnt vmcnt(14)
	ds_write_b32 v68, v65
	s_waitcnt vmcnt(13)
	ds_write_b32 v70, v98
	s_waitcnt vmcnt(12)
	ds_write_b32 v72, v99
	s_waitcnt vmcnt(11)
	ds_write_b32 v74, v100
	s_waitcnt vmcnt(10)
	ds_write_b32 v76, v101
	s_waitcnt vmcnt(9)
	ds_write_b32 v78, v102
	s_waitcnt vmcnt(8)
	ds_write_b32 v80, v103
	s_waitcnt vmcnt(7)
	ds_write_b32 v82, v104
	s_waitcnt vmcnt(6)
	ds_write_b32 v84, v105
	s_waitcnt vmcnt(5)
	ds_write_b32 v86, v106
	s_waitcnt vmcnt(4)
	ds_write_b32 v88, v107
	s_waitcnt vmcnt(3)
	ds_write_b32 v90, v108
	s_waitcnt vmcnt(2)
	ds_write_b32 v92, v109
	s_waitcnt vmcnt(1)
	ds_write_b32 v94, v110
	s_waitcnt vmcnt(0)
	ds_write_b32 v96, v111
	s_cbranch_scc1 .LBB0_51
	s_andn2_b64 vcc, exec, s[38:39]
	s_cbranch_vccz .LBB0_48
	v_mov_b32_e32 v0, 1.0
	v_mov_b32_e32 v40, 1.0
	v_mov_b32_e32 v1, v0
	v_mov_b32_e32 v41, v0
	v_mov_b32_e32 v4, v0
	v_mov_b32_e32 v2, v0
	v_mov_b32_e32 v5, v0
	v_mov_b32_e32 v3, v0
	s_branch .LBB0_49

.LBB0_57:
	s_lshl_b32 s39, s35, 1
	s_lshl_b32 s40, s34, 1
	v_add_u32_e32 v60, s39, v4
	v_add_u32_e32 v58, s40, v5
	v_add_u32_e32 v62, s40, v7
	v_add_u32_e32 v64, s39, v6
	v_add_u32_e32 v66, s40, v25
	v_add_u32_e32 v68, s39, v30
	v_add_u32_e32 v70, s40, v27
	v_add_u32_e32 v72, s39, v36
	v_add_u32_e32 v74, s40, v29
	v_add_u32_e32 v76, s39, v38
	v_add_u32_e32 v78, s40, v31
	v_add_u32_e32 v80, s39, v40
	v_add_u32_e32 v82, s40, v33
	v_add_u32_e32 v84, s39, v42
	v_add_u32_e32 v86, s40, v35
	v_add_u32_e32 v88, s39, v44
	v_ashrrev_i32_e32 v61, 31, v60
	v_ashrrev_i32_e32 v59, 31, v58
	v_ashrrev_i32_e32 v65, 31, v64
	v_ashrrev_i32_e32 v63, 31, v62
	v_ashrrev_i32_e32 v69, 31, v68
	v_ashrrev_i32_e32 v67, 31, v66
	v_ashrrev_i32_e32 v73, 31, v72
	v_ashrrev_i32_e32 v71, 31, v70
	v_ashrrev_i32_e32 v77, 31, v76
	v_ashrrev_i32_e32 v75, 31, v74
	v_ashrrev_i32_e32 v81, 31, v80
	v_ashrrev_i32_e32 v79, 31, v78
	v_ashrrev_i32_e32 v85, 31, v84
	v_ashrrev_i32_e32 v83, 31, v82
	v_ashrrev_i32_e32 v89, 31, v88
	v_ashrrev_i32_e32 v87, 31, v86
	v_lshlrev_b64 v[60:61], 13, v[60:61]
	v_lshlrev_b64 v[58:59], 13, v[58:59]
	v_lshlrev_b64 v[62:63], 13, v[62:63]
	v_lshlrev_b64 v[64:65], 13, v[64:65]
	v_lshlrev_b64 v[66:67], 13, v[66:67]
	v_lshlrev_b64 v[68:69], 13, v[68:69]
	v_lshlrev_b64 v[70:71], 13, v[70:71]
	v_lshlrev_b64 v[72:73], 13, v[72:73]
	v_lshlrev_b64 v[74:75], 13, v[74:75]
	v_lshlrev_b64 v[76:77], 13, v[76:77]
	v_lshlrev_b64 v[78:79], 13, v[78:79]
	v_lshlrev_b64 v[80:81], 13, v[80:81]
	v_lshlrev_b64 v[82:83], 13, v[82:83]
	v_lshlrev_b64 v[84:85], 13, v[84:85]
	v_lshlrev_b64 v[86:87], 13, v[86:87]
	v_lshlrev_b64 v[88:89], 13, v[88:89]
	v_lshl_add_u64 v[60:61], v[2:3], 0, v[60:61]
	v_lshl_add_u64 v[58:59], v[2:3], 0, v[58:59]
	v_lshl_add_u64 v[64:65], v[2:3], 0, v[64:65]
	v_lshl_add_u64 v[62:63], v[2:3], 0, v[62:63]
	v_lshl_add_u64 v[68:69], v[2:3], 0, v[68:69]
	v_lshl_add_u64 v[66:67], v[2:3], 0, v[66:67]
	v_lshl_add_u64 v[72:73], v[2:3], 0, v[72:73]
	v_lshl_add_u64 v[70:71], v[2:3], 0, v[70:71]
	v_lshl_add_u64 v[76:77], v[2:3], 0, v[76:77]
	v_lshl_add_u64 v[74:75], v[2:3], 0, v[74:75]
	v_lshl_add_u64 v[80:81], v[2:3], 0, v[80:81]
	v_lshl_add_u64 v[78:79], v[2:3], 0, v[78:79]
	v_lshl_add_u64 v[84:85], v[2:3], 0, v[84:85]
	v_lshl_add_u64 v[82:83], v[2:3], 0, v[82:83]
	v_lshl_add_u64 v[88:89], v[2:3], 0, v[88:89]
	v_lshl_add_u64 v[86:87], v[2:3], 0, v[86:87]
	global_load_dword v37, v[60:61], off nt
	global_load_dword v52, v[58:59], off nt
	global_load_dword v57, v[64:65], off nt
	global_load_dword v90, v[62:63], off nt
	global_load_dword v91, v[68:69], off nt
	global_load_dword v92, v[66:67], off nt
	global_load_dword v93, v[72:73], off nt
	global_load_dword v94, v[70:71], off nt
	global_load_dword v95, v[76:77], off nt
	global_load_dword v96, v[74:75], off nt
	global_load_dword v97, v[80:81], off nt
	global_load_dword v98, v[78:79], off nt
	global_load_dword v99, v[84:85], off nt
	global_load_dword v100, v[82:83], off nt
	global_load_dword v101, v[88:89], off nt
	global_load_dword v102, v[86:87], off nt
	s_add_i32 s35, s35, 16
	s_add_i32 s34, s34, 16
	s_add_i32 s37, s37, -16
	v_add_u32_e32 v58, s39, v12
	v_add_u32_e32 v60, s40, v9
	v_add_u32_e32 v64, s40, v11
	v_add_u32_e32 v62, s39, v14
	v_add_u32_e32 v68, s40, v13
	v_add_u32_e32 v66, s39, v16
	v_add_u32_e32 v72, s40, v15
	v_add_u32_e32 v70, s39, v18
	v_add_u32_e32 v76, s40, v17
	v_add_u32_e32 v74, s39, v20
	v_add_u32_e32 v80, s40, v19
	v_add_u32_e32 v78, s39, v22
	v_add_u32_e32 v84, s40, v21
	v_add_u32_e32 v82, s39, v24
	v_add_u32_e32 v88, s40, v23
	v_add_u32_e32 v86, s39, v26
	s_cmp_lg_u32 s37, 0
	v_mad_u64_u32 v[58:59], s[40:41], v58, s62, v[32:33]
	v_mad_u64_u32 v[60:61], s[40:41], v60, s62, v[32:33]
	v_mad_u64_u32 v[62:63], s[40:41], v62, s62, v[32:33]
	v_mad_u64_u32 v[64:65], s[40:41], v64, s62, v[32:33]
	v_mad_u64_u32 v[66:67], s[40:41], v66, s62, v[32:33]
	v_mad_u64_u32 v[68:69], s[40:41], v68, s62, v[32:33]
	v_mad_u64_u32 v[70:71], s[40:41], v70, s62, v[32:33]
	v_mad_u64_u32 v[72:73], s[40:41], v72, s62, v[32:33]
	v_mad_u64_u32 v[74:75], s[40:41], v74, s62, v[32:33]
	v_mad_u64_u32 v[76:77], s[40:41], v76, s62, v[32:33]
	v_mad_u64_u32 v[78:79], s[40:41], v78, s62, v[32:33]
	v_mad_u64_u32 v[80:81], s[40:41], v80, s62, v[32:33]
	v_mad_u64_u32 v[82:83], s[40:41], v82, s62, v[32:33]
	v_mad_u64_u32 v[84:85], s[40:41], v84, s62, v[32:33]
	v_mad_u64_u32 v[86:87], s[40:41], v86, s62, v[32:33]
	v_mad_u64_u32 v[88:89], s[40:41], v88, s62, v[32:33]
	s_waitcnt vmcnt(0)
	ds_write_b32 v58, v37
	s_waitcnt vmcnt(14)
	ds_write_b32 v60, v52
	s_waitcnt vmcnt(13)
	ds_write_b32 v62, v57
	s_waitcnt vmcnt(12)
	ds_write_b32 v64, v90
	s_waitcnt vmcnt(11)
	ds_write_b32 v66, v91
	s_waitcnt vmcnt(10)
	ds_write_b32 v68, v92
	s_waitcnt vmcnt(9)
	ds_write_b32 v70, v93
	s_waitcnt vmcnt(8)
	ds_write_b32 v72, v94
	s_waitcnt vmcnt(7)
	ds_write_b32 v74, v95
	s_waitcnt vmcnt(6)
	ds_write_b32 v76, v96
	s_waitcnt vmcnt(5)
	ds_write_b32 v78, v97
	s_waitcnt vmcnt(4)
	ds_write_b32 v80, v98
	s_waitcnt vmcnt(3)
	ds_write_b32 v82, v99
	s_waitcnt vmcnt(2)
	ds_write_b32 v84, v100
	s_waitcnt vmcnt(1)
	ds_write_b32 v86, v101
	s_waitcnt vmcnt(0)
	ds_write_b32 v88, v102
	s_cbranch_scc1 .LBB0_57
	s_waitcnt lgkmcnt(0)
	ds_read2_b32 v[6:7], v39 offset1:8
	ds_read2_b32 v[30:31], v39 offset0:33 offset1:41
	ds_read2_b32 v[36:37], v39 offset0:66 offset1:74
	ds_read2_b32 v[58:59], v39 offset0:99 offset1:107
	ds_read2_b32 v[60:61], v39 offset0:132 offset1:140
	ds_read2_b32 v[62:63], v39 offset0:165 offset1:173
	s_waitcnt lgkmcnt(5)
	v_bfe_u32 v2, v6, 16, 1
	v_add3_u32 v2, v6, v2, s63
	s_waitcnt lgkmcnt(4)
	v_bfe_u32 v3, v30, 16, 1
	v_lshrrev_b32_e32 v2, 16, v2
	v_add3_u32 v3, v30, v3, s63
	v_and_or_b32 v2, v3, s43, v2
	s_waitcnt lgkmcnt(3)
	v_bfe_u32 v3, v36, 16, 1
	v_add3_u32 v3, v36, v3, s63
	s_waitcnt lgkmcnt(2)
	v_bfe_u32 v4, v58, 16, 1
	ds_read2_b32 v[64:65], v39 offset0:198 offset1:206
	v_lshrrev_b32_e32 v3, 16, v3
	v_add3_u32 v4, v58, v4, s63
	ds_read2_b32 v[66:67], v39 offset0:231 offset1:239
	v_and_or_b32 v3, v4, s43, v3
	s_waitcnt lgkmcnt(3)
	v_bfe_u32 v4, v60, 16, 1
	v_add3_u32 v4, v60, v4, s63
	s_waitcnt lgkmcnt(2)
	v_bfe_u32 v5, v62, 16, 1
	v_lshrrev_b32_e32 v4, 16, v4
	v_add3_u32 v5, v62, v5, s63
	v_and_or_b32 v4, v5, s43, v4
	s_waitcnt lgkmcnt(1)
	v_bfe_u32 v5, v64, 16, 1
	v_add3_u32 v5, v64, v5, s63
	s_waitcnt lgkmcnt(0)
	v_bfe_u32 v6, v66, 16, 1
	v_add_u32_e32 v25, s38, v43
	v_lshrrev_b32_e32 v5, 16, v5
	v_add3_u32 v6, v66, v6, s63
	v_and_or_b32 v5, v6, s43, v5
	v_and_or_b32 v6, v25, s42, v41
	v_ashrrev_i32_e32 v25, 7, v25
	v_mul_lo_u32 v68, v25, s7
	s_ashr_i32 s37, s36, 31
	v_ashrrev_i32_e32 v69, 31, v68
	v_lshl_add_u64 v[68:69], v[68:69], 0, s[36:37]
	v_lshrrev_b32_e32 v6, 3, v6
	v_lshlrev_b64 v[68:69], 14, v[68:69]
	v_or_b32_e32 v6, v6, v45
	v_lshl_or_b32 v70, v6, 10, v46
	v_mov_b32_e32 v71, v8
	v_lshl_add_u64 v[68:69], s[28:29], 0, v[68:69]
	v_lshl_add_u64 v[68:69], v[68:69], 0, v[70:71]
	global_store_dwordx4 v[68:69], v[2:5], off
	v_bfe_u32 v6, v67, 16, 1
	v_add3_u32 v6, v67, v6, s63
	v_bfe_u32 v2, v7, 16, 1
	v_add3_u32 v2, v7, v2, s63
	v_bfe_u32 v3, v31, 16, 1
	v_lshrrev_b32_e32 v2, 16, v2
	v_add3_u32 v3, v31, v3, s63
	v_and_or_b32 v2, v3, s43, v2
	v_bfe_u32 v3, v37, 16, 1
	v_add3_u32 v3, v37, v3, s63
	v_bfe_u32 v4, v59, 16, 1
	v_lshrrev_b32_e32 v3, 16, v3
	v_add3_u32 v4, v59, v4, s63
	v_and_or_b32 v3, v4, s43, v3
	v_bfe_u32 v4, v61, 16, 1
	v_add3_u32 v4, v61, v4, s63
	v_bfe_u32 v5, v63, 16, 1
	v_lshrrev_b32_e32 v4, 16, v4
	v_add3_u32 v5, v63, v5, s63
	v_and_or_b32 v4, v5, s43, v4
	v_bfe_u32 v5, v65, 16, 1
	v_add3_u32 v5, v65, v5, s63
	v_lshrrev_b32_e32 v5, 16, v5
	v_and_or_b32 v5, v6, s43, v5
	v_add_u32_e32 v6, s38, v47
	v_and_or_b32 v25, v6, s42, v48
	v_ashrrev_i32_e32 v6, 7, v6
	v_mul_lo_u32 v6, v6, s7
	v_ashrrev_i32_e32 v7, 31, v6
	v_lshl_add_u64 v[6:7], v[6:7], 0, s[36:37]
	v_lshrrev_b32_e32 v25, 3, v25
	v_lshlrev_b64 v[6:7], 14, v[6:7]
	v_or_b32_e32 v25, v25, v45
	v_lshl_or_b32 v30, v25, 10, v53
	v_mov_b32_e32 v31, v8
	v_lshl_add_u64 v[6:7], s[28:29], 0, v[6:7]
	ds_read2_b32 v[36:37], v39 offset0:16 offset1:24
	v_lshl_add_u64 v[6:7], v[6:7], 0, v[30:31]
	global_store_dwordx4 v[6:7], v[2:5], off
	ds_read2_b32 v[6:7], v39 offset0:49 offset1:57
	ds_read2_b32 v[30:31], v39 offset0:82 offset1:90
	ds_read2_b32 v[58:59], v39 offset0:115 offset1:123
	s_waitcnt lgkmcnt(3)
	v_bfe_u32 v2, v36, 16, 1
	v_add3_u32 v2, v36, v2, s63
	s_waitcnt lgkmcnt(2)
	v_bfe_u32 v3, v6, 16, 1
	ds_read2_b32 v[60:61], v39 offset0:148 offset1:156
	v_lshrrev_b32_e32 v2, 16, v2
	v_add3_u32 v3, v6, v3, s63
	ds_read2_b32 v[62:63], v39 offset0:181 offset1:189
	v_and_or_b32 v2, v3, s43, v2
	s_waitcnt lgkmcnt(3)
	v_bfe_u32 v3, v30, 16, 1
	v_add3_u32 v3, v30, v3, s63
	s_waitcnt lgkmcnt(2)
	v_bfe_u32 v4, v58, 16, 1
	ds_read2_b32 v[64:65], v39 offset0:214 offset1:222
	v_lshrrev_b32_e32 v3, 16, v3
	v_add3_u32 v4, v58, v4, s63
	ds_read2_b32 v[66:67], v39 offset0:247 offset1:255
	v_and_or_b32 v3, v4, s43, v3
	s_waitcnt lgkmcnt(3)
	v_bfe_u32 v4, v60, 16, 1
	v_add3_u32 v4, v60, v4, s63
	s_waitcnt lgkmcnt(2)
	v_bfe_u32 v5, v62, 16, 1
	v_lshrrev_b32_e32 v4, 16, v4
	v_add3_u32 v5, v62, v5, s63
	v_and_or_b32 v4, v5, s43, v4
	s_waitcnt lgkmcnt(1)
	v_bfe_u32 v5, v64, 16, 1
	v_add3_u32 v5, v64, v5, s63
	s_waitcnt lgkmcnt(0)
	v_bfe_u32 v6, v66, 16, 1
	v_lshrrev_b32_e32 v5, 16, v5
	v_add3_u32 v6, v66, v6, s63
	v_and_or_b32 v5, v6, s43, v5
	v_add_u32_e32 v6, s38, v49
	v_and_or_b32 v25, v6, s42, v54
	v_ashrrev_i32_e32 v6, 7, v6
	v_mul_lo_u32 v68, v6, s7
	v_ashrrev_i32_e32 v69, 31, v68
	v_lshl_add_u64 v[68:69], v[68:69], 0, s[36:37]
	v_lshrrev_b32_e32 v6, 3, v25
	v_lshlrev_b64 v[68:69], 14, v[68:69]
	v_or_b32_e32 v6, v6, v45
	v_lshl_or_b32 v70, v6, 10, v55
	v_lshl_add_u64 v[68:69], s[28:29], 0, v[68:69]
	v_lshl_add_u64 v[68:69], v[68:69], 0, v[70:71]
	global_store_dwordx4 v[68:69], v[2:5], off
	v_bfe_u32 v6, v67, 16, 1
	v_add3_u32 v6, v67, v6, s63
	v_bfe_u32 v2, v37, 16, 1
	v_add3_u32 v2, v37, v2, s63
	v_bfe_u32 v3, v7, 16, 1
	v_lshrrev_b32_e32 v2, 16, v2
	v_add3_u32 v3, v7, v3, s63
	v_and_or_b32 v2, v3, s43, v2
	v_bfe_u32 v3, v31, 16, 1
	v_add3_u32 v3, v31, v3, s63
	v_bfe_u32 v4, v59, 16, 1
	v_lshrrev_b32_e32 v3, 16, v3
	v_add3_u32 v4, v59, v4, s63
	v_and_or_b32 v3, v4, s43, v3
	v_bfe_u32 v4, v61, 16, 1
	v_add3_u32 v4, v61, v4, s63
	v_bfe_u32 v5, v63, 16, 1
	v_lshrrev_b32_e32 v4, 16, v4
	v_add3_u32 v5, v63, v5, s63
	v_and_or_b32 v4, v5, s43, v4
	v_bfe_u32 v5, v65, 16, 1
	v_add3_u32 v5, v65, v5, s63
	v_lshrrev_b32_e32 v5, 16, v5
	v_and_or_b32 v5, v6, s43, v5
	v_add_u32_e32 v6, s38, v50
	v_and_or_b32 v25, v6, s42, v56
	v_ashrrev_i32_e32 v6, 7, v6
	v_mul_lo_u32 v6, v6, s7
	v_ashrrev_i32_e32 v7, 31, v6
	v_lshl_add_u64 v[6:7], v[6:7], 0, s[36:37]
	v_lshrrev_b32_e32 v25, 3, v25
	v_lshlrev_b64 v[6:7], 14, v[6:7]
	v_or_b32_e32 v25, v25, v45
	v_lshl_or_b32 v30, v25, 10, v51
	v_mov_b32_e32 v31, v8
	v_lshl_add_u64 v[6:7], s[28:29], 0, v[6:7]
	v_lshl_add_u64 v[6:7], v[6:7], 0, v[30:31]
	global_store_dwordx4 v[6:7], v[2:5], off
	s_waitcnt lgkmcnt(0)
	s_add_i32 s25, s25, s22
	s_cmpk_lt_i32 s25, 0x1600
	s_cbranch_scc1 .LBB0_56
	s_load_dwordx2 s[34:35], s[10:11], 0x18
	s_load_dwordx2 s[36:37], s[10:11], 0x8
	s_add_u32 s28, s8, 0x1000000
	s_addc_u32 s29, s9, 0
	v_lshlrev_b32_e32 v30, 2, v28
	s_waitcnt lgkmcnt(0)
	s_add_u32 s34, s34, s18
	s_addc_u32 s35, s35, s19
	s_lshl_b64 s[14:15], s[14:15], 2
	s_add_u32 s38, s36, s14
	s_addc_u32 s39, s37, s15
	v_mov_b32_e32 v31, v8
	s_cmp_lg_u64 s[36:37], 0
	v_mov_b32_e32 v35, v8
	v_lshl_add_u64 v[36:37], s[34:35], 0, v[30:31]
	s_cselect_b64 s[14:15], -1, 0
	v_lshl_add_u64 v[28:29], s[38:39], 0, v[34:35]
	s_mov_b32 s25, s51
	s_branch .LBB0_62

.LBB0_63:
	s_lshl_b32 s41, s36, 1
	s_lshl_b32 s44, s35, 1
	v_add_u32_e32 v57, s41, v2
	v_add_u32_e32 v52, s44, v3
	v_add_u32_e32 v64, s44, v5
	v_add_u32_e32 v62, s41, v4
	v_add_u32_e32 v68, s44, v7
	v_add_u32_e32 v66, s41, v6
	v_add_u32_e32 v72, s44, v25
	v_add_u32_e32 v70, s41, v34
	v_add_u32_e32 v76, s44, v27
	v_add_u32_e32 v74, s41, v38
	v_add_u32_e32 v80, s44, v31
	v_add_u32_e32 v78, s41, v40
	v_add_u32_e32 v84, s44, v33
	v_add_u32_e32 v82, s41, v42
	v_add_u32_e32 v88, s44, v35
	v_add_u32_e32 v86, s41, v44
	v_mad_i64_i32 v[58:59], s[42:43], v57, s20, v[0:1]
	v_mad_i64_i32 v[60:61], s[42:43], v52, s20, v[0:1]
	v_mad_i64_i32 v[62:63], s[42:43], v62, s20, v[0:1]
	v_mad_i64_i32 v[64:65], s[42:43], v64, s20, v[0:1]
	v_mad_i64_i32 v[66:67], s[42:43], v66, s20, v[0:1]
	v_mad_i64_i32 v[68:69], s[42:43], v68, s20, v[0:1]
	v_mad_i64_i32 v[70:71], s[42:43], v70, s20, v[0:1]
	v_mad_i64_i32 v[72:73], s[42:43], v72, s20, v[0:1]
	v_mad_i64_i32 v[74:75], s[42:43], v74, s20, v[0:1]
	v_mad_i64_i32 v[76:77], s[42:43], v76, s20, v[0:1]
	v_mad_i64_i32 v[78:79], s[42:43], v78, s20, v[0:1]
	v_mad_i64_i32 v[80:81], s[42:43], v80, s20, v[0:1]
	v_mad_i64_i32 v[82:83], s[42:43], v82, s20, v[0:1]
	v_mad_i64_i32 v[84:85], s[42:43], v84, s20, v[0:1]
	v_mad_i64_i32 v[86:87], s[42:43], v86, s20, v[0:1]
	v_mad_i64_i32 v[88:89], s[42:43], v88, s20, v[0:1]
	global_load_dword v52, v[58:59], off nt
	global_load_dword v57, v[60:61], off nt
	global_load_dword v90, v[62:63], off nt
	global_load_dword v91, v[64:65], off nt
	global_load_dword v92, v[66:67], off nt
	global_load_dword v93, v[68:69], off nt
	global_load_dword v94, v[70:71], off nt
	global_load_dword v95, v[72:73], off nt
	global_load_dword v96, v[74:75], off nt
	global_load_dword v97, v[76:77], off nt
	global_load_dword v98, v[78:79], off nt
	global_load_dword v99, v[80:81], off nt
	global_load_dword v100, v[82:83], off nt
	global_load_dword v101, v[84:85], off nt
	global_load_dword v102, v[86:87], off nt
	global_load_dword v103, v[88:89], off nt
	s_add_i32 s36, s36, 16
	s_add_i32 s35, s35, 16
	s_add_i32 s37, s37, -16
	v_add_u32_e32 v58, s41, v12
	v_add_u32_e32 v60, s44, v9
	v_add_u32_e32 v64, s44, v11
	v_add_u32_e32 v62, s41, v14
	v_add_u32_e32 v68, s44, v13
	v_add_u32_e32 v66, s41, v16
	v_add_u32_e32 v72, s44, v15
	v_add_u32_e32 v70, s41, v18
	v_add_u32_e32 v76, s44, v17
	v_add_u32_e32 v74, s41, v20
	v_add_u32_e32 v80, s44, v19
	v_add_u32_e32 v78, s41, v22
	v_add_u32_e32 v84, s44, v21
	v_add_u32_e32 v82, s41, v24
	v_add_u32_e32 v88, s44, v23
	v_add_u32_e32 v86, s41, v26
	s_cmp_lg_u32 s37, 0
	v_mad_u64_u32 v[58:59], s[42:43], v58, s62, v[32:33]
	v_mad_u64_u32 v[60:61], s[42:43], v60, s62, v[32:33]
	v_mad_u64_u32 v[62:63], s[42:43], v62, s62, v[32:33]
	v_mad_u64_u32 v[64:65], s[42:43], v64, s62, v[32:33]
	v_mad_u64_u32 v[66:67], s[42:43], v66, s62, v[32:33]
	v_mad_u64_u32 v[68:69], s[42:43], v68, s62, v[32:33]
	v_mad_u64_u32 v[70:71], s[42:43], v70, s62, v[32:33]
	v_mad_u64_u32 v[72:73], s[42:43], v72, s62, v[32:33]
	v_mad_u64_u32 v[74:75], s[42:43], v74, s62, v[32:33]
	v_mad_u64_u32 v[76:77], s[42:43], v76, s62, v[32:33]
	v_mad_u64_u32 v[78:79], s[42:43], v78, s62, v[32:33]
	v_mad_u64_u32 v[80:81], s[42:43], v80, s62, v[32:33]
	v_mad_u64_u32 v[82:83], s[42:43], v82, s62, v[32:33]
	v_mad_u64_u32 v[84:85], s[42:43], v84, s62, v[32:33]
	v_mad_u64_u32 v[86:87], s[42:43], v86, s62, v[32:33]
	v_mad_u64_u32 v[88:89], s[42:43], v88, s62, v[32:33]
	s_waitcnt vmcnt(15)
	ds_write_b32 v58, v52
	s_waitcnt vmcnt(14)
	ds_write_b32 v60, v57
	s_waitcnt vmcnt(13)
	ds_write_b32 v62, v90
	s_waitcnt vmcnt(12)
	ds_write_b32 v64, v91
	s_waitcnt vmcnt(11)
	ds_write_b32 v66, v92
	s_waitcnt vmcnt(10)
	ds_write_b32 v68, v93
	s_waitcnt vmcnt(9)
	ds_write_b32 v70, v94
	s_waitcnt vmcnt(8)
	ds_write_b32 v72, v95
	s_waitcnt vmcnt(7)
	ds_write_b32 v74, v96
	s_waitcnt vmcnt(6)
	ds_write_b32 v76, v97
	s_waitcnt vmcnt(5)
	ds_write_b32 v78, v98
	s_waitcnt vmcnt(4)
	ds_write_b32 v80, v99
	s_waitcnt vmcnt(3)
	ds_write_b32 v82, v100
	s_waitcnt vmcnt(2)
	ds_write_b32 v84, v101
	s_waitcnt vmcnt(1)
	ds_write_b32 v86, v102
	s_waitcnt vmcnt(0)
	ds_write_b32 v88, v103
	s_cbranch_scc1 .LBB0_63
	v_cndmask_b32_e64 v0, 0, 1, s[14:15]
	v_cmp_ne_u32_e64 s[36:37], 1, v0
	s_andn2_b64 vcc, exec, s[14:15]
	s_cbranch_vccz .LBB0_60
	v_mov_b32_e32 v0, 1.0
	v_mov_b32_e32 v34, 1.0
	v_mov_b32_e32 v1, v0
	v_mov_b32_e32 v35, v0
	v_mov_b32_e32 v4, v0
	v_mov_b32_e32 v2, v0
	v_mov_b32_e32 v5, v0
	v_mov_b32_e32 v3, v0
	s_branch .LBB0_61

.LBB0_70:
	s_lshl_b32 s39, s35, 1
	s_lshl_b32 s42, s19, 1
	v_add_u32_e32 v52, s39, v2
	v_add_u32_e32 v44, s42, v3
	v_add_u32_e32 v57, s42, v5
	v_add_u32_e32 v62, s39, v4
	v_add_u32_e32 v68, s42, v7
	v_add_u32_e32 v66, s39, v6
	v_add_u32_e32 v72, s42, v25
	v_add_u32_e32 v70, s39, v34
	v_add_u32_e32 v76, s42, v27
	v_add_u32_e32 v74, s39, v36
	v_add_u32_e32 v80, s42, v33
	v_add_u32_e32 v78, s39, v38
	v_add_u32_e32 v84, s42, v35
	v_add_u32_e32 v82, s39, v40
	v_add_u32_e32 v88, s42, v37
	v_add_u32_e32 v86, s39, v42
	v_mad_i64_i32 v[58:59], s[40:41], v52, s20, v[0:1]
	v_mad_i64_i32 v[60:61], s[40:41], v44, s20, v[0:1]
	v_mad_i64_i32 v[62:63], s[40:41], v62, s20, v[0:1]
	v_mad_i64_i32 v[64:65], s[40:41], v57, s20, v[0:1]
	v_mad_i64_i32 v[66:67], s[40:41], v66, s20, v[0:1]
	v_mad_i64_i32 v[68:69], s[40:41], v68, s20, v[0:1]
	v_mad_i64_i32 v[70:71], s[40:41], v70, s20, v[0:1]
	v_mad_i64_i32 v[72:73], s[40:41], v72, s20, v[0:1]
	v_mad_i64_i32 v[74:75], s[40:41], v74, s20, v[0:1]
	v_mad_i64_i32 v[76:77], s[40:41], v76, s20, v[0:1]
	v_mad_i64_i32 v[78:79], s[40:41], v78, s20, v[0:1]
	v_mad_i64_i32 v[80:81], s[40:41], v80, s20, v[0:1]
	v_mad_i64_i32 v[82:83], s[40:41], v82, s20, v[0:1]
	v_mad_i64_i32 v[84:85], s[40:41], v84, s20, v[0:1]
	v_mad_i64_i32 v[86:87], s[40:41], v86, s20, v[0:1]
	v_mad_i64_i32 v[88:89], s[40:41], v88, s20, v[0:1]
	global_load_dword v44, v[58:59], off nt
	global_load_dword v52, v[60:61], off nt
	global_load_dword v57, v[62:63], off nt
	global_load_dword v90, v[64:65], off nt
	global_load_dword v91, v[66:67], off nt
	global_load_dword v92, v[68:69], off nt
	global_load_dword v93, v[70:71], off nt
	global_load_dword v94, v[72:73], off nt
	global_load_dword v95, v[74:75], off nt
	global_load_dword v96, v[76:77], off nt
	global_load_dword v97, v[78:79], off nt
	global_load_dword v98, v[80:81], off nt
	global_load_dword v99, v[82:83], off nt
	global_load_dword v100, v[84:85], off nt
	global_load_dword v101, v[86:87], off nt
	global_load_dword v102, v[88:89], off nt
	s_add_i32 s35, s35, 16
	s_add_i32 s19, s19, 16
	s_add_i32 s38, s38, -16
	v_add_u32_e32 v58, s39, v12
	v_add_u32_e32 v60, s42, v9
	v_add_u32_e32 v64, s42, v11
	v_add_u32_e32 v62, s39, v14
	v_add_u32_e32 v68, s42, v13
	v_add_u32_e32 v66, s39, v16
	v_add_u32_e32 v72, s42, v15
	v_add_u32_e32 v70, s39, v18
	v_add_u32_e32 v76, s42, v17
	v_add_u32_e32 v74, s39, v20
	v_add_u32_e32 v80, s42, v19
	v_add_u32_e32 v78, s39, v22
	v_add_u32_e32 v84, s42, v21
	v_add_u32_e32 v82, s39, v24
	v_add_u32_e32 v88, s42, v23
	v_add_u32_e32 v86, s39, v26
	s_cmp_lg_u32 s38, 0
	v_mad_u64_u32 v[58:59], s[40:41], v58, s62, v[32:33]
	v_mad_u64_u32 v[60:61], s[40:41], v60, s62, v[32:33]
	v_mad_u64_u32 v[62:63], s[40:41], v62, s62, v[32:33]
	v_mad_u64_u32 v[64:65], s[40:41], v64, s62, v[32:33]
	v_mad_u64_u32 v[66:67], s[40:41], v66, s62, v[32:33]
	v_mad_u64_u32 v[68:69], s[40:41], v68, s62, v[32:33]
	v_mad_u64_u32 v[70:71], s[40:41], v70, s62, v[32:33]
	v_mad_u64_u32 v[72:73], s[40:41], v72, s62, v[32:33]
	v_mad_u64_u32 v[74:75], s[40:41], v74, s62, v[32:33]
	v_mad_u64_u32 v[76:77], s[40:41], v76, s62, v[32:33]
	v_mad_u64_u32 v[78:79], s[40:41], v78, s62, v[32:33]
	v_mad_u64_u32 v[80:81], s[40:41], v80, s62, v[32:33]
	v_mad_u64_u32 v[82:83], s[40:41], v82, s62, v[32:33]
	v_mad_u64_u32 v[84:85], s[40:41], v84, s62, v[32:33]
	v_mad_u64_u32 v[86:87], s[40:41], v86, s62, v[32:33]
	v_mad_u64_u32 v[88:89], s[40:41], v88, s62, v[32:33]
	s_waitcnt vmcnt(15)
	ds_write_b32 v58, v44
	s_waitcnt vmcnt(14)
	ds_write_b32 v60, v52
	s_waitcnt vmcnt(13)
	ds_write_b32 v62, v57
	s_waitcnt vmcnt(12)
	ds_write_b32 v64, v90
	s_waitcnt vmcnt(11)
	ds_write_b32 v66, v91
	s_waitcnt vmcnt(10)
	ds_write_b32 v68, v92
	s_waitcnt vmcnt(9)
	ds_write_b32 v70, v93
	s_waitcnt vmcnt(8)
	ds_write_b32 v72, v94
	s_waitcnt vmcnt(7)
	ds_write_b32 v74, v95
	s_waitcnt vmcnt(6)
	ds_write_b32 v76, v96
	s_waitcnt vmcnt(5)
	ds_write_b32 v78, v97
	s_waitcnt vmcnt(4)
	ds_write_b32 v80, v98
	s_waitcnt vmcnt(3)
	ds_write_b32 v82, v99
	s_waitcnt vmcnt(2)
	ds_write_b32 v84, v100
	s_waitcnt vmcnt(1)
	ds_write_b32 v86, v101
	s_waitcnt vmcnt(0)
	ds_write_b32 v88, v102
	s_cbranch_scc1 .LBB0_70
	s_and_b64 vcc, exec, s[36:37]
	s_cbranch_vccz .LBB0_67
	v_mov_b32_e32 v0, 1.0
	v_mov_b32_e32 v34, 1.0
	v_mov_b32_e32 v1, v0
	v_mov_b32_e32 v35, v0
	v_mov_b32_e32 v4, v0
	v_mov_b32_e32 v2, v0
	v_mov_b32_e32 v5, v0
	v_mov_b32_e32 v3, v0
	s_branch .LBB0_68
